# all GEMM-loop setprio flips removed, second-buffer LDS base adds hoisted, fp8 fragment LDS reads made bank-conflict-free with the bf16 k-map
# speedup vs baseline: 1.0569x; 1.0569x over previous
.LBB0_215:
	s_ashr_i32 s13, s12, 31
	s_lshl_b64 s[16:17], s[12:13], 21
	s_add_u32 s16, s70, s16
	s_addc_u32 s17, s71, s17
	s_and_b64 s[18:19], s[2:3], exec
	s_cselect_b32 s13, s17, s1
	s_cselect_b32 s24, s16, s0
	s_ashr_i32 s15, s14, 31
	s_lshl_b64 s[18:19], s[14:15], 21
	s_add_u32 s18, s6, s18
	s_addc_u32 s19, s7, s19
	s_and_b64 s[22:23], s[2:3], exec
	s_cselect_b32 s15, s19, s21
	s_cselect_b32 s25, s18, s20
	s_add_u32 s0, s0, 0x100080
	s_addc_u32 s1, s1, 0
	s_add_u32 s27, s20, 0x100
	v_mov_b32_e32 v2, 0
	s_addc_u32 s29, s21, 0
	s_mov_b32 s30, -2
	v_mov_b32_e32 v3, v2
	v_mov_b32_e32 v4, v2
	v_mov_b32_e32 v5, v2
	v_mov_b32_e32 v6, v2
	v_mov_b32_e32 v7, v2
	v_mov_b32_e32 v8, v2
	v_mov_b32_e32 v9, v2
	v_mov_b32_e32 v18, v2
	v_mov_b32_e32 v19, v2
	v_mov_b32_e32 v20, v2
	v_mov_b32_e32 v21, v2
	v_mov_b32_e32 v22, v2
	v_mov_b32_e32 v23, v2
	v_mov_b32_e32 v24, v2
	v_mov_b32_e32 v25, v2
	v_mov_b32_e32 v34, v2
	v_mov_b32_e32 v35, v2
	v_mov_b32_e32 v36, v2
	v_mov_b32_e32 v37, v2
	v_mov_b32_e32 v38, v2
	v_mov_b32_e32 v39, v2
	v_mov_b32_e32 v40, v2
	v_mov_b32_e32 v41, v2
	v_mov_b32_e32 v50, v2
	v_mov_b32_e32 v51, v2
	v_mov_b32_e32 v52, v2
	v_mov_b32_e32 v53, v2
	v_mov_b32_e32 v54, v2
	v_mov_b32_e32 v55, v2
	v_mov_b32_e32 v56, v2
	v_mov_b32_e32 v57, v2
	v_mov_b32_e32 v10, v2
	v_mov_b32_e32 v11, v2
	v_mov_b32_e32 v12, v2
	v_mov_b32_e32 v13, v2
	v_mov_b32_e32 v14, v2
	v_mov_b32_e32 v15, v2
	v_mov_b32_e32 v16, v2
	v_mov_b32_e32 v17, v2
	v_mov_b32_e32 v26, v2
	v_mov_b32_e32 v27, v2
	v_mov_b32_e32 v28, v2
	v_mov_b32_e32 v29, v2
	v_mov_b32_e32 v30, v2
	v_mov_b32_e32 v31, v2
	v_mov_b32_e32 v32, v2
	v_mov_b32_e32 v33, v2
	v_mov_b32_e32 v42, v2
	v_mov_b32_e32 v43, v2
	v_mov_b32_e32 v44, v2
	v_mov_b32_e32 v45, v2
	v_mov_b32_e32 v46, v2
	v_mov_b32_e32 v47, v2
	v_mov_b32_e32 v48, v2
	v_mov_b32_e32 v49, v2
	v_mov_b32_e32 v58, v2
	v_mov_b32_e32 v59, v2
	v_mov_b32_e32 v60, v2
	v_mov_b32_e32 v61, v2
	v_mov_b32_e32 v62, v2
	v_mov_b32_e32 v63, v2
	v_mov_b32_e32 v64, v2
	v_mov_b32_e32 v65, v2
	v_mov_b32_e32 v66, v2
	v_mov_b32_e32 v67, v2
	v_mov_b32_e32 v68, v2
	v_mov_b32_e32 v69, v2
	v_mov_b32_e32 v70, v2
	v_mov_b32_e32 v71, v2
	v_mov_b32_e32 v72, v2
	v_mov_b32_e32 v73, v2
	v_mov_b32_e32 v78, v2
	v_mov_b32_e32 v79, v2
	v_mov_b32_e32 v80, v2
	v_mov_b32_e32 v81, v2
	v_mov_b32_e32 v86, v2
	v_mov_b32_e32 v87, v2
	v_mov_b32_e32 v88, v2
	v_mov_b32_e32 v89, v2
	v_mov_b32_e32 v94, v2
	v_mov_b32_e32 v95, v2
	v_mov_b32_e32 v96, v2
	v_mov_b32_e32 v97, v2
	v_mov_b32_e32 v102, v2
	v_mov_b32_e32 v103, v2
	v_mov_b32_e32 v104, v2
	v_mov_b32_e32 v105, v2
	v_mov_b32_e32 v110, v2
	v_mov_b32_e32 v111, v2
	v_mov_b32_e32 v112, v2
	v_mov_b32_e32 v113, v2
	v_mov_b32_e32 v118, v2
	v_mov_b32_e32 v119, v2
	v_mov_b32_e32 v120, v2
	v_mov_b32_e32 v121, v2
	v_mov_b32_e32 v74, v2
	v_mov_b32_e32 v75, v2
	v_mov_b32_e32 v76, v2
	v_mov_b32_e32 v77, v2
	v_mov_b32_e32 v82, v2
	v_mov_b32_e32 v83, v2
	v_mov_b32_e32 v84, v2
	v_mov_b32_e32 v85, v2
	v_mov_b32_e32 v90, v2
	v_mov_b32_e32 v91, v2
	v_mov_b32_e32 v92, v2
	v_mov_b32_e32 v93, v2
	v_mov_b32_e32 v98, v2
	v_mov_b32_e32 v99, v2
	v_mov_b32_e32 v100, v2
	v_mov_b32_e32 v101, v2
	v_mov_b32_e32 v106, v2
	v_mov_b32_e32 v107, v2
	v_mov_b32_e32 v108, v2
	v_mov_b32_e32 v109, v2
	v_mov_b32_e32 v114, v2
	v_mov_b32_e32 v115, v2
	v_mov_b32_e32 v116, v2
	v_mov_b32_e32 v117, v2
	v_mov_b32_e32 v122, v2
	v_mov_b32_e32 v123, v2
	v_mov_b32_e32 v124, v2
	v_mov_b32_e32 v125, v2
	v_mov_b32_e32 v126, v2
	v_mov_b32_e32 v127, v2
	v_mov_b32_e32 v128, v2
	v_mov_b32_e32 v129, v2
	v_add_u32_e32 v246, 0x18000, v158
	v_add_u32_e32 v247, 0x1c000, v158
.LBB0_216:
	ds_read_b128 v[152:155], v160
	ds_read_b128 v[164:167], v160 offset:1024
	ds_read_b128 v[168:171], v160 offset:2048
	ds_read_b128 v[172:175], v160 offset:3072
	ds_read_b128 v[176:179], v161
	ds_read_b128 v[180:183], v161 offset:1024
	ds_read_b128 v[184:187], v161 offset:2048
	ds_read_b128 v[188:191], v161 offset:3072
	s_add_u32 s20, s0, 0xfff00080
	s_addc_u32 s21, s1, -1
	s_cmp_eq_u32 s30, 60
	s_cselect_b32 s23, s13, s21
	s_cselect_b32 s22, s24, s20
	s_cselect_b32 s21, s15, s29
	s_cselect_b32 s20, s25, s27
	s_add_i32 m0, s39, 0xc000
	ds_read_b128 v[192:195], v162
	ds_read_b128 v[196:199], v162 offset:1024
	ds_read_b128 v[200:203], v162 offset:2048
	ds_read_b128 v[204:207], v162 offset:3072
	ds_read_b128 v[208:211], v162 offset:4096
	ds_read_b128 v[212:215], v162 offset:5120
	ds_read_b128 v[216:219], v162 offset:6144
	ds_read_b128 v[220:223], v162 offset:7168
	global_load_lds_dwordx4 v140, s[0:1]
	s_add_i32 m0, s39, 0xe000
	s_nop 0
	global_load_lds_dwordx4 v142, s[0:1]
	s_waitcnt vmcnt(8)
	s_waitcnt lgkmcnt(0)
	s_barrier
	v_mfma_f32_16x16x32_bf16 v[126:129], v[152:155], v[192:195], v[126:129]
	v_mfma_f32_16x16x32_bf16 v[126:129], v[164:167], v[196:199], v[126:129]
	v_mfma_f32_16x16x32_bf16 v[122:125], v[168:171], v[192:195], v[122:125]
	v_mfma_f32_16x16x32_bf16 v[122:125], v[172:175], v[196:199], v[122:125]
	v_mfma_f32_16x16x32_bf16 v[114:117], v[152:155], v[200:203], v[114:117]
	v_mfma_f32_16x16x32_bf16 v[114:117], v[164:167], v[204:207], v[114:117]
	v_mfma_f32_16x16x32_bf16 v[106:109], v[168:171], v[200:203], v[106:109]
	v_mfma_f32_16x16x32_bf16 v[106:109], v[172:175], v[204:207], v[106:109]
	v_mfma_f32_16x16x32_bf16 v[98:101], v[152:155], v[208:211], v[98:101]
	v_mfma_f32_16x16x32_bf16 v[98:101], v[164:167], v[212:215], v[98:101]
	v_mfma_f32_16x16x32_bf16 v[90:93], v[168:171], v[208:211], v[90:93]
	v_mfma_f32_16x16x32_bf16 v[90:93], v[172:175], v[212:215], v[90:93]
	v_mfma_f32_16x16x32_bf16 v[82:85], v[152:155], v[216:219], v[82:85]
	v_mfma_f32_16x16x32_bf16 v[82:85], v[164:167], v[220:223], v[82:85]
	v_mfma_f32_16x16x32_bf16 v[74:77], v[168:171], v[216:219], v[74:77]
	v_mfma_f32_16x16x32_bf16 v[74:77], v[172:175], v[220:223], v[74:77]
	v_mfma_f32_16x16x32_bf16 v[118:121], v[176:179], v[192:195], v[118:121]
	v_mfma_f32_16x16x32_bf16 v[118:121], v[180:183], v[196:199], v[118:121]
	v_mfma_f32_16x16x32_bf16 v[110:113], v[184:187], v[192:195], v[110:113]
	v_mfma_f32_16x16x32_bf16 v[110:113], v[188:191], v[196:199], v[110:113]
	v_mfma_f32_16x16x32_bf16 v[102:105], v[176:179], v[200:203], v[102:105]
	v_mfma_f32_16x16x32_bf16 v[102:105], v[180:183], v[204:207], v[102:105]
	v_mfma_f32_16x16x32_bf16 v[94:97], v[184:187], v[200:203], v[94:97]
	v_mfma_f32_16x16x32_bf16 v[94:97], v[188:191], v[204:207], v[94:97]
	v_mfma_f32_16x16x32_bf16 v[86:89], v[176:179], v[208:211], v[86:89]
	v_mfma_f32_16x16x32_bf16 v[86:89], v[180:183], v[212:215], v[86:89]
	v_mfma_f32_16x16x32_bf16 v[78:81], v[184:187], v[208:211], v[78:81]
	v_mfma_f32_16x16x32_bf16 v[78:81], v[188:191], v[212:215], v[78:81]
	v_mfma_f32_16x16x32_bf16 v[70:73], v[176:179], v[216:219], v[70:73]
	v_mfma_f32_16x16x32_bf16 v[70:73], v[180:183], v[220:223], v[70:73]
	v_mfma_f32_16x16x32_bf16 v[66:69], v[184:187], v[216:219], v[66:69]
	v_mfma_f32_16x16x32_bf16 v[66:69], v[188:191], v[220:223], v[66:69]
	s_barrier
	s_add_i32 s31, s49, s38
	s_mov_b32 m0, s31
	ds_read_b128 v[192:195], v162 offset:16384
	ds_read_b128 v[196:199], v162 offset:17408
	ds_read_b128 v[200:203], v162 offset:18432
	ds_read_b128 v[204:207], v162 offset:19456
	ds_read_b128 v[208:211], v162 offset:20480
	ds_read_b128 v[212:215], v162 offset:21504
	ds_read_b128 v[216:219], v162 offset:22528
	ds_read_b128 v[220:223], v162 offset:23552
	global_load_lds_dwordx4 v132, s[20:21]
	s_add_i32 m0, s31, 0x2000
	s_add_u32 s34, s20, 0x100000
	s_addc_u32 s35, s21, 0
	s_add_i32 s31, s50, s38
	global_load_lds_dwordx4 v136, s[20:21]
	s_mov_b32 m0, s31
	global_load_lds_dwordx4 v132, s[34:35]
	s_add_i32 m0, s31, 0x2000
	s_nop 0
	global_load_lds_dwordx4 v136, s[34:35]
	s_mov_b32 m0, s39
	s_nop 0
	global_load_lds_dwordx4 v130, s[22:23]
	s_mov_b32 m0, s40
	s_nop 0
	global_load_lds_dwordx4 v134, s[22:23]
	s_waitcnt vmcnt(8)
	s_waitcnt lgkmcnt(0)
	s_barrier
	v_mfma_f32_16x16x32_bf16 v[62:65], v[152:155], v[192:195], v[62:65]
	v_mfma_f32_16x16x32_bf16 v[62:65], v[164:167], v[196:199], v[62:65]
	v_mfma_f32_16x16x32_bf16 v[58:61], v[168:171], v[192:195], v[58:61]
	v_mfma_f32_16x16x32_bf16 v[58:61], v[172:175], v[196:199], v[58:61]
	v_mfma_f32_16x16x32_bf16 v[46:49], v[152:155], v[200:203], v[46:49]
	v_mfma_f32_16x16x32_bf16 v[46:49], v[164:167], v[204:207], v[46:49]
	v_mfma_f32_16x16x32_bf16 v[42:45], v[168:171], v[200:203], v[42:45]
	v_mfma_f32_16x16x32_bf16 v[42:45], v[172:175], v[204:207], v[42:45]
	v_mfma_f32_16x16x32_bf16 v[30:33], v[152:155], v[208:211], v[30:33]
	v_mfma_f32_16x16x32_bf16 v[30:33], v[164:167], v[212:215], v[30:33]
	v_mfma_f32_16x16x32_bf16 v[26:29], v[168:171], v[208:211], v[26:29]
	v_mfma_f32_16x16x32_bf16 v[26:29], v[172:175], v[212:215], v[26:29]
	v_mfma_f32_16x16x32_bf16 v[14:17], v[152:155], v[216:219], v[14:17]
	v_mfma_f32_16x16x32_bf16 v[14:17], v[164:167], v[220:223], v[14:17]
	v_mfma_f32_16x16x32_bf16 v[10:13], v[168:171], v[216:219], v[10:13]
	v_mfma_f32_16x16x32_bf16 v[10:13], v[172:175], v[220:223], v[10:13]
	v_mfma_f32_16x16x32_bf16 v[54:57], v[176:179], v[192:195], v[54:57]
	v_mfma_f32_16x16x32_bf16 v[54:57], v[180:183], v[196:199], v[54:57]
	v_mfma_f32_16x16x32_bf16 v[50:53], v[184:187], v[192:195], v[50:53]
	v_mfma_f32_16x16x32_bf16 v[50:53], v[188:191], v[196:199], v[50:53]
	v_mfma_f32_16x16x32_bf16 v[38:41], v[176:179], v[200:203], v[38:41]
	v_mfma_f32_16x16x32_bf16 v[38:41], v[180:183], v[204:207], v[38:41]
	v_mfma_f32_16x16x32_bf16 v[34:37], v[184:187], v[200:203], v[34:37]
	v_mfma_f32_16x16x32_bf16 v[34:37], v[188:191], v[204:207], v[34:37]
	v_mfma_f32_16x16x32_bf16 v[22:25], v[176:179], v[208:211], v[22:25]
	v_mfma_f32_16x16x32_bf16 v[22:25], v[180:183], v[212:215], v[22:25]
	v_mfma_f32_16x16x32_bf16 v[18:21], v[184:187], v[208:211], v[18:21]
	v_mfma_f32_16x16x32_bf16 v[18:21], v[188:191], v[212:215], v[18:21]
	v_mfma_f32_16x16x32_bf16 v[6:9], v[176:179], v[216:219], v[6:9]
	v_mfma_f32_16x16x32_bf16 v[6:9], v[180:183], v[220:223], v[6:9]
	v_mfma_f32_16x16x32_bf16 v[2:5], v[184:187], v[216:219], v[2:5]
	v_mfma_f32_16x16x32_bf16 v[2:5], v[188:191], v[220:223], v[2:5]
	s_barrier
	s_add_i32 s31, 0, 0x18000
	s_add_i32 s33, 0, 0x1c000
	ds_read_b128 v[152:155], v246
	ds_read_b128 v[164:167], v246 offset:1024
	ds_read_b128 v[168:171], v246 offset:2048
	ds_read_b128 v[172:175], v246 offset:3072
	ds_read_b128 v[176:179], v247
	ds_read_b128 v[180:183], v247 offset:1024
	ds_read_b128 v[184:187], v247 offset:2048
	ds_read_b128 v[188:191], v247 offset:3072
	s_add_u32 s98, s22, 0x80
	s_addc_u32 s99, s23, 0
	s_add_u32 s22, s22, 0x100000
	s_addc_u32 s23, s23, 0
	s_mov_b32 m0, s41
	ds_read_b128 v[192:195], v162 offset:32768
	ds_read_b128 v[196:199], v162 offset:33792
	ds_read_b128 v[200:203], v162 offset:34816
	ds_read_b128 v[204:207], v162 offset:35840
	ds_read_b128 v[208:211], v162 offset:36864
	ds_read_b128 v[212:215], v162 offset:37888
	ds_read_b128 v[216:219], v162 offset:38912
	ds_read_b128 v[220:223], v162 offset:39936
	global_load_lds_dwordx4 v130, s[22:23]
	s_mov_b32 m0, s42
	s_nop 0
	global_load_lds_dwordx4 v134, s[22:23]
	s_waitcnt vmcnt(8)
	s_waitcnt lgkmcnt(0)
	s_barrier
	v_mfma_f32_16x16x32_bf16 v[126:129], v[152:155], v[192:195], v[126:129]
	v_mfma_f32_16x16x32_bf16 v[126:129], v[164:167], v[196:199], v[126:129]
	v_mfma_f32_16x16x32_bf16 v[122:125], v[168:171], v[192:195], v[122:125]
	v_mfma_f32_16x16x32_bf16 v[122:125], v[172:175], v[196:199], v[122:125]
	v_mfma_f32_16x16x32_bf16 v[114:117], v[152:155], v[200:203], v[114:117]
	v_mfma_f32_16x16x32_bf16 v[114:117], v[164:167], v[204:207], v[114:117]
	v_mfma_f32_16x16x32_bf16 v[106:109], v[168:171], v[200:203], v[106:109]
	v_mfma_f32_16x16x32_bf16 v[106:109], v[172:175], v[204:207], v[106:109]
	v_mfma_f32_16x16x32_bf16 v[98:101], v[152:155], v[208:211], v[98:101]
	v_mfma_f32_16x16x32_bf16 v[98:101], v[164:167], v[212:215], v[98:101]
	v_mfma_f32_16x16x32_bf16 v[90:93], v[168:171], v[208:211], v[90:93]
	v_mfma_f32_16x16x32_bf16 v[90:93], v[172:175], v[212:215], v[90:93]
	v_mfma_f32_16x16x32_bf16 v[82:85], v[152:155], v[216:219], v[82:85]
	v_mfma_f32_16x16x32_bf16 v[82:85], v[164:167], v[220:223], v[82:85]
	v_mfma_f32_16x16x32_bf16 v[74:77], v[168:171], v[216:219], v[74:77]
	v_mfma_f32_16x16x32_bf16 v[74:77], v[172:175], v[220:223], v[74:77]
	v_mfma_f32_16x16x32_bf16 v[118:121], v[176:179], v[192:195], v[118:121]
	v_mfma_f32_16x16x32_bf16 v[118:121], v[180:183], v[196:199], v[118:121]
	v_mfma_f32_16x16x32_bf16 v[110:113], v[184:187], v[192:195], v[110:113]
	v_mfma_f32_16x16x32_bf16 v[110:113], v[188:191], v[196:199], v[110:113]
	v_mfma_f32_16x16x32_bf16 v[102:105], v[176:179], v[200:203], v[102:105]
	v_mfma_f32_16x16x32_bf16 v[102:105], v[180:183], v[204:207], v[102:105]
	v_mfma_f32_16x16x32_bf16 v[94:97], v[184:187], v[200:203], v[94:97]
	v_mfma_f32_16x16x32_bf16 v[94:97], v[188:191], v[204:207], v[94:97]
	v_mfma_f32_16x16x32_bf16 v[86:89], v[176:179], v[208:211], v[86:89]
	v_mfma_f32_16x16x32_bf16 v[86:89], v[180:183], v[212:215], v[86:89]
	v_mfma_f32_16x16x32_bf16 v[78:81], v[184:187], v[208:211], v[78:81]
	v_mfma_f32_16x16x32_bf16 v[78:81], v[188:191], v[212:215], v[78:81]
	v_mfma_f32_16x16x32_bf16 v[70:73], v[176:179], v[216:219], v[70:73]
	v_mfma_f32_16x16x32_bf16 v[70:73], v[180:183], v[220:223], v[70:73]
	v_mfma_f32_16x16x32_bf16 v[66:69], v[184:187], v[216:219], v[66:69]
	v_mfma_f32_16x16x32_bf16 v[66:69], v[188:191], v[220:223], v[66:69]
	s_barrier
	s_add_i32 s22, s31, s38
	s_mov_b32 m0, s22
	ds_read_b128 v[192:195], v162 offset:49152
	ds_read_b128 v[196:199], v162 offset:50176
	ds_read_b128 v[200:203], v162 offset:51200
	ds_read_b128 v[204:207], v162 offset:52224
	ds_read_b128 v[208:211], v162 offset:53248
	ds_read_b128 v[212:215], v162 offset:54272
	ds_read_b128 v[216:219], v162 offset:55296
	ds_read_b128 v[220:223], v162 offset:56320
	s_add_u32 s20, s20, 0x80
	s_addc_u32 s21, s21, 0
	global_load_lds_dwordx4 v132, s[20:21]
	s_add_i32 m0, s22, 0x2000
	s_add_i32 s22, s33, s38
	global_load_lds_dwordx4 v136, s[20:21]
	s_add_u32 s20, s20, 0x100000
	s_addc_u32 s21, s21, 0
	s_mov_b32 m0, s22
	s_nop 0
	global_load_lds_dwordx4 v132, s[20:21]
	s_add_i32 m0, s22, 0x2000
	s_nop 0
	global_load_lds_dwordx4 v136, s[20:21]
	s_mov_b32 m0, s45
	s_nop 0
	global_load_lds_dwordx4 v130, s[98:99]
	s_mov_b32 m0, s46
	s_nop 0
	global_load_lds_dwordx4 v134, s[98:99]
	s_waitcnt vmcnt(8)
	s_waitcnt lgkmcnt(0)
	s_barrier
	v_mfma_f32_16x16x32_bf16 v[62:65], v[152:155], v[192:195], v[62:65]
	v_mfma_f32_16x16x32_bf16 v[62:65], v[164:167], v[196:199], v[62:65]
	v_mfma_f32_16x16x32_bf16 v[58:61], v[168:171], v[192:195], v[58:61]
	v_mfma_f32_16x16x32_bf16 v[58:61], v[172:175], v[196:199], v[58:61]
	v_mfma_f32_16x16x32_bf16 v[46:49], v[152:155], v[200:203], v[46:49]
	v_mfma_f32_16x16x32_bf16 v[46:49], v[164:167], v[204:207], v[46:49]
	v_mfma_f32_16x16x32_bf16 v[42:45], v[168:171], v[200:203], v[42:45]
	v_mfma_f32_16x16x32_bf16 v[42:45], v[172:175], v[204:207], v[42:45]
	v_mfma_f32_16x16x32_bf16 v[30:33], v[152:155], v[208:211], v[30:33]
	v_mfma_f32_16x16x32_bf16 v[30:33], v[164:167], v[212:215], v[30:33]
	v_mfma_f32_16x16x32_bf16 v[26:29], v[168:171], v[208:211], v[26:29]
	v_mfma_f32_16x16x32_bf16 v[26:29], v[172:175], v[212:215], v[26:29]
	v_mfma_f32_16x16x32_bf16 v[14:17], v[152:155], v[216:219], v[14:17]
	v_mfma_f32_16x16x32_bf16 v[14:17], v[164:167], v[220:223], v[14:17]
	v_mfma_f32_16x16x32_bf16 v[10:13], v[168:171], v[216:219], v[10:13]
	v_mfma_f32_16x16x32_bf16 v[10:13], v[172:175], v[220:223], v[10:13]
	v_mfma_f32_16x16x32_bf16 v[54:57], v[176:179], v[192:195], v[54:57]
	v_mfma_f32_16x16x32_bf16 v[54:57], v[180:183], v[196:199], v[54:57]
	v_mfma_f32_16x16x32_bf16 v[50:53], v[184:187], v[192:195], v[50:53]
	v_mfma_f32_16x16x32_bf16 v[50:53], v[188:191], v[196:199], v[50:53]
	v_mfma_f32_16x16x32_bf16 v[38:41], v[176:179], v[200:203], v[38:41]
	v_mfma_f32_16x16x32_bf16 v[38:41], v[180:183], v[204:207], v[38:41]
	v_mfma_f32_16x16x32_bf16 v[34:37], v[184:187], v[200:203], v[34:37]
	v_mfma_f32_16x16x32_bf16 v[34:37], v[188:191], v[204:207], v[34:37]
	v_mfma_f32_16x16x32_bf16 v[22:25], v[176:179], v[208:211], v[22:25]
	v_mfma_f32_16x16x32_bf16 v[22:25], v[180:183], v[212:215], v[22:25]
	v_mfma_f32_16x16x32_bf16 v[18:21], v[184:187], v[208:211], v[18:21]
	v_mfma_f32_16x16x32_bf16 v[18:21], v[188:191], v[212:215], v[18:21]
	v_mfma_f32_16x16x32_bf16 v[6:9], v[176:179], v[216:219], v[6:9]
	v_mfma_f32_16x16x32_bf16 v[6:9], v[180:183], v[220:223], v[6:9]
	v_mfma_f32_16x16x32_bf16 v[2:5], v[184:187], v[216:219], v[2:5]
	v_mfma_f32_16x16x32_bf16 v[2:5], v[188:191], v[220:223], v[2:5]
	s_barrier
	s_add_i32 s30, s30, 2
	s_add_u32 s0, s0, 0x100
	s_addc_u32 s1, s1, 0
	s_add_u32 s27, s27, 0x100
	s_addc_u32 s29, s29, 0
	s_cmp_gt_u32 s30, 61
	s_cbranch_scc0 .LBB0_216
	s_and_b64 vcc, exec, s[10:11]
	s_cbranch_vccz .LBB0_219
	s_barrier

.LBB0_265:
	v_bfe_u32 v11, v10, 5, 1
	v_lshlrev_b32_e32 v12, 1, v10
	v_lshlrev_b32_e32 v13, 6, v10
	v_lshlrev_b32_e32 v10, 2, v10
	v_and_b32_e32 v12, 32, v12
	v_and_b32_e32 v13, 0x3c0, v13
	v_and_b32_e32 v10, 32, v10
	s_lshl_b32 s42, s6, 6
	v_or_b32_e32 v14, v13, v12
	s_lshl_b32 s6, s6, 13
	v_lshlrev_b32_e32 v15, 10, v11
	v_bitop3_b32 v12, v13, v10, v12 bitop3:0x36
	v_or3_b32 v12, s6, v15, v12
	s_lshl_b32 s3, s3, 5
	s_mov_b64 s[6:7], 0x80
	s_and_b32 s43, s3, 0x60
	s_add_i32 m0, s19, 0x18000
	v_lshl_add_u64 v[8:9], v[8:9], 0, s[6:7]
	s_lshr_b32 s3, s43, 3
	s_waitcnt vmcnt(2)
	s_barrier
	global_load_lds_dwordx4 v[8:9], off
	v_lshl_add_u64 v[6:7], v[6:7], 0, s[6:7]
	s_add_i32 m0, s19, 0x1a000
	s_add_i32 s44, s19, 0x8000
	s_add_i32 s45, s19, 0xa000
	global_load_lds_dwordx4 v[6:7], off
	v_lshl_add_u64 v[2:3], v[2:3], 0, s[6:7]
	s_mov_b32 m0, s44
	s_add_u32 s8, s0, 0x80080
	global_load_lds_dwordx4 v[2:3], off
	v_lshl_add_u64 v[2:3], v[4:5], 0, s[6:7]
	s_mov_b32 m0, s45
	s_addc_u32 s9, s1, 0
	global_load_lds_dwordx4 v[2:3], off
	s_add_i32 m0, s19, 0x1c000
	v_lshl_add_u64 v[2:3], s[8:9], 0, v[168:169]
	global_load_lds_dwordx4 v[2:3], off
	v_lshl_add_u64 v[2:3], s[8:9], 0, v[170:171]
	s_add_i32 m0, s19, 0x1e000
	v_or_b32_e32 v11, s3, v11
	global_load_lds_dwordx4 v[2:3], off
	v_lshlrev_b32_e32 v11, 10, v11
	s_waitcnt vmcnt(6)
	s_cmpk_lt_u32 s2, 0x100
	v_bitop3_b32 v182, v11, v14, v10 bitop3:0xf6
	s_cselect_b64 s[8:9], -1, 0
	s_add_i32 s48, 0, 0x10000
	s_add_i32 s49, 0, 0x14000
	s_ashr_i32 s46, s88, 31
	s_ashr_i32 s47, s92, 31
	v_mov_b64_e32 v[164:165], 0xa00
	v_mov_b64_e32 v[166:167], 0x9ff
	v_and_b32_e32 v250, 15, v0
	v_lshlrev_b32_e32 v250, 6, v250
	v_bfe_u32 v251, v0, 4, 1
	v_lshl_or_b32 v250, v251, 4, v250
	v_lshrrev_b32_e32 v251, 5, v0
	v_lshrrev_b32_e32 v252, 3, v0
	v_xor_b32_e32 v251, v251, v252
	v_and_b32_e32 v251, 1, v251
	v_lshl_or_b32 v250, v251, 5, v250
	v_and_b32_e32 v182, 0xf000, v182
	v_or_b32_e32 v182, v182, v250
	v_and_b32_e32 v12, 0xf000, v12
	v_or_b32_e32 v12, v12, v250
	v_add_u32_e32 v183, s48, v182
	v_add_u32_e32 v184, s49, v182
	v_add_u32_e32 v185, 0, v12
	v_mov_b32_e32 v186, 0x7f7f7f7f
	s_mov_b32 s50, 0x400000
	s_barrier
	s_branch .LBB0_268

.LBB0_270:
	s_ashr_i32 s13, s12, 31
	s_lshl_b64 s[14:15], s[12:13], 20
	s_add_u32 s14, s79, s14
	s_addc_u32 s15, s93, s15
	s_and_b64 s[16:17], s[2:3], exec
	s_cselect_b32 s13, s15, s21
	s_cselect_b32 s25, s14, s20
	s_ashr_i32 s11, s10, 31
	s_lshl_b64 s[16:17], s[10:11], 20
	s_add_u32 s16, s76, s16
	s_addc_u32 s17, s77, s17
	s_and_b64 s[22:23], s[2:3], exec
	s_cselect_b32 s11, s17, s1
	s_cselect_b32 s26, s16, s0
	s_add_u32 s20, s20, 0x80080
	s_addc_u32 s21, s21, 0
	s_add_u32 s27, s0, 0x100
	v_mov_b32_e32 v34, 0
	v_mov_b32_e32 v173, v163
	v_mov_b32_e32 v169, v163
	v_mov_b32_e32 v171, v163
	s_addc_u32 s28, s1, 0
	s_mov_b32 s29, -2
	v_mov_b32_e32 v35, v34
	v_mov_b32_e32 v36, v34
	v_mov_b32_e32 v37, v34
	v_mov_b32_e32 v38, v34
	v_mov_b32_e32 v39, v34
	v_mov_b32_e32 v40, v34
	v_mov_b32_e32 v41, v34
	v_mov_b32_e32 v50, v34
	v_mov_b32_e32 v51, v34
	v_mov_b32_e32 v52, v34
	v_mov_b32_e32 v53, v34
	v_mov_b32_e32 v54, v34
	v_mov_b32_e32 v55, v34
	v_mov_b32_e32 v56, v34
	v_mov_b32_e32 v57, v34
	v_mov_b32_e32 v66, v34
	v_mov_b32_e32 v67, v34
	v_mov_b32_e32 v68, v34
	v_mov_b32_e32 v69, v34
	v_mov_b32_e32 v70, v34
	v_mov_b32_e32 v71, v34
	v_mov_b32_e32 v72, v34
	v_mov_b32_e32 v73, v34
	v_mov_b32_e32 v82, v34
	v_mov_b32_e32 v83, v34
	v_mov_b32_e32 v84, v34
	v_mov_b32_e32 v85, v34
	v_mov_b32_e32 v86, v34
	v_mov_b32_e32 v87, v34
	v_mov_b32_e32 v88, v34
	v_mov_b32_e32 v89, v34
	v_mov_b32_e32 v42, v34
	v_mov_b32_e32 v43, v34
	v_mov_b32_e32 v44, v34
	v_mov_b32_e32 v45, v34
	v_mov_b32_e32 v46, v34
	v_mov_b32_e32 v47, v34
	v_mov_b32_e32 v48, v34
	v_mov_b32_e32 v49, v34
	v_mov_b32_e32 v58, v34
	v_mov_b32_e32 v59, v34
	v_mov_b32_e32 v60, v34
	v_mov_b32_e32 v61, v34
	v_mov_b32_e32 v62, v34
	v_mov_b32_e32 v63, v34
	v_mov_b32_e32 v64, v34
	v_mov_b32_e32 v65, v34
	v_mov_b32_e32 v74, v34
	v_mov_b32_e32 v75, v34
	v_mov_b32_e32 v76, v34
	v_mov_b32_e32 v77, v34
	v_mov_b32_e32 v78, v34
	v_mov_b32_e32 v79, v34
	v_mov_b32_e32 v80, v34
	v_mov_b32_e32 v81, v34
	v_mov_b32_e32 v90, v34
	v_mov_b32_e32 v91, v34
	v_mov_b32_e32 v92, v34
	v_mov_b32_e32 v93, v34
	v_mov_b32_e32 v94, v34
	v_mov_b32_e32 v95, v34
	v_mov_b32_e32 v96, v34
	v_mov_b32_e32 v97, v34
	v_mov_b32_e32 v98, v34
	v_mov_b32_e32 v99, v34
	v_mov_b32_e32 v100, v34
	v_mov_b32_e32 v101, v34
	v_mov_b32_e32 v102, v34
	v_mov_b32_e32 v103, v34
	v_mov_b32_e32 v104, v34
	v_mov_b32_e32 v105, v34
	v_mov_b32_e32 v110, v34
	v_mov_b32_e32 v111, v34
	v_mov_b32_e32 v112, v34
	v_mov_b32_e32 v113, v34
	v_mov_b32_e32 v118, v34
	v_mov_b32_e32 v119, v34
	v_mov_b32_e32 v120, v34
	v_mov_b32_e32 v121, v34
	v_mov_b32_e32 v126, v34
	v_mov_b32_e32 v127, v34
	v_mov_b32_e32 v128, v34
	v_mov_b32_e32 v129, v34
	v_mov_b32_e32 v134, v34
	v_mov_b32_e32 v135, v34
	v_mov_b32_e32 v136, v34
	v_mov_b32_e32 v137, v34
	v_mov_b32_e32 v142, v34
	v_mov_b32_e32 v143, v34
	v_mov_b32_e32 v144, v34
	v_mov_b32_e32 v145, v34
	v_mov_b32_e32 v150, v34
	v_mov_b32_e32 v151, v34
	v_mov_b32_e32 v152, v34
	v_mov_b32_e32 v153, v34
	v_mov_b32_e32 v106, v34
	v_mov_b32_e32 v107, v34
	v_mov_b32_e32 v108, v34
	v_mov_b32_e32 v109, v34
	v_mov_b32_e32 v114, v34
	v_mov_b32_e32 v115, v34
	v_mov_b32_e32 v116, v34
	v_mov_b32_e32 v117, v34
	v_mov_b32_e32 v122, v34
	v_mov_b32_e32 v123, v34
	v_mov_b32_e32 v124, v34
	v_mov_b32_e32 v125, v34
	v_mov_b32_e32 v130, v34
	v_mov_b32_e32 v131, v34
	v_mov_b32_e32 v132, v34
	v_mov_b32_e32 v133, v34
	v_mov_b32_e32 v138, v34
	v_mov_b32_e32 v139, v34
	v_mov_b32_e32 v140, v34
	v_mov_b32_e32 v141, v34
	v_mov_b32_e32 v146, v34
	v_mov_b32_e32 v147, v34
	v_mov_b32_e32 v148, v34
	v_mov_b32_e32 v149, v34
	v_mov_b32_e32 v154, v34
	v_mov_b32_e32 v155, v34
	v_mov_b32_e32 v156, v34
	v_mov_b32_e32 v157, v34
	v_mov_b32_e32 v158, v34
	v_mov_b32_e32 v159, v34
	v_mov_b32_e32 v160, v34
	v_mov_b32_e32 v161, v34
	v_add_u32_e32 v246, 0x18000, v182
	v_add_u32_e32 v247, 0x1c000, v182
.LBB0_271:
	ds_read_b128 v[26:29], v183
	ds_read_b128 v[30:33], v183 offset:1024
	ds_read_b128 v[18:21], v183 offset:2048
	ds_read_b128 v[22:25], v183 offset:3072
	ds_read_b128 v[10:13], v184
	ds_read_b128 v[14:17], v184 offset:1024
	ds_read_b128 v[2:5], v184 offset:2048
	ds_read_b128 v[6:9], v184 offset:3072
	s_add_u32 s0, s20, 0xfff80080
	s_addc_u32 s1, s21, -1
	s_cmp_eq_u32 s29, 28
	s_cselect_b32 s23, s13, s1
	s_cselect_b32 s22, s25, s0
	s_cselect_b32 s1, s11, s28
	s_cselect_b32 s0, s26, s27
	s_add_i32 m0, s19, 0xc000
	ds_read_b128 v[174:177], v185
	ds_read_b128 v[178:181], v185 offset:1024
	ds_read_b128 v[188:191], v185 offset:2048
	ds_read_b128 v[192:195], v185 offset:3072
	ds_read_b128 v[196:199], v185 offset:4096
	ds_read_b128 v[200:203], v185 offset:5120
	ds_read_b128 v[204:207], v185 offset:6144
	ds_read_b128 v[208:211], v185 offset:7168
	global_load_lds_dwordx4 v162, s[20:21]
	s_add_i32 m0, s19, 0xe000
	s_nop 0
	global_load_lds_dwordx4 v172, s[20:21]
	s_waitcnt vmcnt(8)
	s_waitcnt lgkmcnt(0)
	s_barrier
	v_mfma_f32_16x16x128_f8f6f4 v[158:161], v[26:33], v[174:181], v[158:161]
	v_mfma_f32_16x16x128_f8f6f4 v[154:157], v[18:25], v[174:181], v[154:157]
	v_mfma_f32_16x16x128_f8f6f4 v[146:149], v[26:33], v[188:195], v[146:149]
	v_mfma_f32_16x16x128_f8f6f4 v[138:141], v[18:25], v[188:195], v[138:141]
	v_mfma_f32_16x16x128_f8f6f4 v[130:133], v[26:33], v[196:203], v[130:133]
	v_mfma_f32_16x16x128_f8f6f4 v[122:125], v[18:25], v[196:203], v[122:125]
	v_mfma_f32_16x16x128_f8f6f4 v[114:117], v[26:33], v[204:211], v[114:117]
	v_mfma_f32_16x16x128_f8f6f4 v[106:109], v[18:25], v[204:211], v[106:109]
	v_mfma_f32_16x16x128_f8f6f4 v[150:153], v[10:17], v[174:181], v[150:153]
	v_mfma_f32_16x16x128_f8f6f4 v[142:145], v[2:9], v[174:181], v[142:145]
	v_mfma_f32_16x16x128_f8f6f4 v[134:137], v[10:17], v[188:195], v[134:137]
	v_mfma_f32_16x16x128_f8f6f4 v[126:129], v[2:9], v[188:195], v[126:129]
	v_mfma_f32_16x16x128_f8f6f4 v[118:121], v[10:17], v[196:203], v[118:121]
	v_mfma_f32_16x16x128_f8f6f4 v[110:113], v[2:9], v[196:203], v[110:113]
	v_mfma_f32_16x16x128_f8f6f4 v[102:105], v[10:17], v[204:211], v[102:105]
	v_mfma_f32_16x16x128_f8f6f4 v[98:101], v[2:9], v[204:211], v[98:101]
	s_barrier
	s_add_i32 s30, s48, s37
	s_mov_b32 m0, s30
	ds_read_b128 v[188:191], v185 offset:16384
	ds_read_b128 v[192:195], v185 offset:17408
	ds_read_b128 v[196:199], v185 offset:18432
	ds_read_b128 v[200:203], v185 offset:19456
	ds_read_b128 v[204:207], v185 offset:20480
	ds_read_b128 v[208:211], v185 offset:21504
	ds_read_b128 v[212:215], v185 offset:22528
	ds_read_b128 v[216:219], v185 offset:23552
	global_load_lds_dwordx4 v168, s[0:1]
	s_add_i32 m0, s30, 0x2000
	s_add_u32 s30, s0, 0x80000
	s_addc_u32 s31, s1, 0
	s_add_i32 s33, s49, s37
	global_load_lds_dwordx4 v170, s[0:1]
	s_mov_b32 m0, s33
	global_load_lds_dwordx4 v168, s[30:31]
	s_add_i32 m0, s33, 0x2000
	s_nop 0
	global_load_lds_dwordx4 v170, s[30:31]
	s_mov_b32 m0, s19
	s_nop 0
	global_load_lds_dwordx4 v162, s[22:23]
	s_mov_b32 m0, s38
	s_nop 0
	global_load_lds_dwordx4 v172, s[22:23]
	s_waitcnt vmcnt(8)
	s_waitcnt lgkmcnt(0)
	s_barrier
	v_mfma_f32_16x16x128_f8f6f4 v[94:97], v[26:33], v[188:195], v[94:97]
	v_mfma_f32_16x16x128_f8f6f4 v[90:93], v[18:25], v[188:195], v[90:93]
	v_mfma_f32_16x16x128_f8f6f4 v[78:81], v[26:33], v[196:203], v[78:81]
	v_mfma_f32_16x16x128_f8f6f4 v[74:77], v[18:25], v[196:203], v[74:77]
	v_mfma_f32_16x16x128_f8f6f4 v[62:65], v[26:33], v[204:211], v[62:65]
	v_mfma_f32_16x16x128_f8f6f4 v[58:61], v[18:25], v[204:211], v[58:61]
	v_mfma_f32_16x16x128_f8f6f4 v[46:49], v[26:33], v[212:219], v[46:49]
	v_mfma_f32_16x16x128_f8f6f4 v[42:45], v[18:25], v[212:219], v[42:45]
	v_mfma_f32_16x16x128_f8f6f4 v[86:89], v[10:17], v[188:195], v[86:89]
	v_mfma_f32_16x16x128_f8f6f4 v[82:85], v[2:9], v[188:195], v[82:85]
	v_mfma_f32_16x16x128_f8f6f4 v[70:73], v[10:17], v[196:203], v[70:73]
	v_mfma_f32_16x16x128_f8f6f4 v[66:69], v[2:9], v[196:203], v[66:69]
	v_mfma_f32_16x16x128_f8f6f4 v[54:57], v[10:17], v[204:211], v[54:57]
	v_mfma_f32_16x16x128_f8f6f4 v[50:53], v[2:9], v[204:211], v[50:53]
	v_mfma_f32_16x16x128_f8f6f4 v[38:41], v[10:17], v[212:219], v[38:41]
	v_mfma_f32_16x16x128_f8f6f4 v[34:37], v[2:9], v[212:219], v[34:37]
	s_barrier
	s_add_i32 s30, 0, 0x18000
	s_add_i32 s31, 0, 0x1c000
	ds_read_b128 v[2:5], v246
	ds_read_b128 v[6:9], v246 offset:1024
	ds_read_b128 v[10:13], v246 offset:2048
	ds_read_b128 v[14:17], v246 offset:3072
	ds_read_b128 v[18:21], v247
	ds_read_b128 v[22:25], v247 offset:1024
	ds_read_b128 v[26:29], v247 offset:2048
	ds_read_b128 v[30:33], v247 offset:3072
	s_add_u32 s98, s22, 0x80
	s_addc_u32 s99, s23, 0
	s_add_u32 s22, s22, 0x80000
	s_addc_u32 s23, s23, 0
	s_mov_b32 m0, s39
	ds_read_b128 v[188:191], v185 offset:32768
	ds_read_b128 v[192:195], v185 offset:33792
	ds_read_b128 v[196:199], v185 offset:34816
	ds_read_b128 v[200:203], v185 offset:35840
	ds_read_b128 v[204:207], v185 offset:36864
	ds_read_b128 v[208:211], v185 offset:37888
	ds_read_b128 v[212:215], v185 offset:38912
	ds_read_b128 v[216:219], v185 offset:39936
	global_load_lds_dwordx4 v162, s[22:23]
	s_mov_b32 m0, s40
	s_nop 0
	global_load_lds_dwordx4 v172, s[22:23]
	s_waitcnt vmcnt(8)
	s_waitcnt lgkmcnt(0)
	s_barrier
	v_mfma_f32_16x16x128_f8f6f4 v[158:161], v[2:9], v[188:195], v[158:161]
	v_mfma_f32_16x16x128_f8f6f4 v[154:157], v[10:17], v[188:195], v[154:157]
	v_mfma_f32_16x16x128_f8f6f4 v[146:149], v[2:9], v[196:203], v[146:149]
	v_mfma_f32_16x16x128_f8f6f4 v[138:141], v[10:17], v[196:203], v[138:141]
	v_mfma_f32_16x16x128_f8f6f4 v[130:133], v[2:9], v[204:211], v[130:133]
	v_mfma_f32_16x16x128_f8f6f4 v[122:125], v[10:17], v[204:211], v[122:125]
	v_mfma_f32_16x16x128_f8f6f4 v[114:117], v[2:9], v[212:219], v[114:117]
	v_mfma_f32_16x16x128_f8f6f4 v[106:109], v[10:17], v[212:219], v[106:109]
	v_mfma_f32_16x16x128_f8f6f4 v[150:153], v[18:25], v[188:195], v[150:153]
	v_mfma_f32_16x16x128_f8f6f4 v[142:145], v[26:33], v[188:195], v[142:145]
	v_mfma_f32_16x16x128_f8f6f4 v[134:137], v[18:25], v[196:203], v[134:137]
	v_mfma_f32_16x16x128_f8f6f4 v[126:129], v[26:33], v[196:203], v[126:129]
	v_mfma_f32_16x16x128_f8f6f4 v[118:121], v[18:25], v[204:211], v[118:121]
	v_mfma_f32_16x16x128_f8f6f4 v[110:113], v[26:33], v[204:211], v[110:113]
	v_mfma_f32_16x16x128_f8f6f4 v[102:105], v[18:25], v[212:219], v[102:105]
	v_mfma_f32_16x16x128_f8f6f4 v[98:101], v[26:33], v[212:219], v[98:101]
	s_barrier
	s_add_i32 s22, s30, s37
	s_mov_b32 m0, s22
	ds_read_b128 v[188:191], v185 offset:49152
	ds_read_b128 v[192:195], v185 offset:50176
	ds_read_b128 v[196:199], v185 offset:51200
	ds_read_b128 v[200:203], v185 offset:52224
	ds_read_b128 v[204:207], v185 offset:53248
	ds_read_b128 v[208:211], v185 offset:54272
	ds_read_b128 v[212:215], v185 offset:55296
	ds_read_b128 v[216:219], v185 offset:56320
	s_add_u32 s0, s0, 0x80
	s_addc_u32 s1, s1, 0
	global_load_lds_dwordx4 v168, s[0:1]
	s_add_i32 m0, s22, 0x2000
	s_add_i32 s22, s31, s37
	global_load_lds_dwordx4 v170, s[0:1]
	s_add_u32 s0, s0, 0x80000
	s_addc_u32 s1, s1, 0
	s_mov_b32 m0, s22
	s_nop 0
	global_load_lds_dwordx4 v168, s[0:1]
	s_add_i32 m0, s22, 0x2000
	s_nop 0
	global_load_lds_dwordx4 v170, s[0:1]
	s_mov_b32 m0, s44
	s_nop 0
	global_load_lds_dwordx4 v162, s[98:99]
	s_mov_b32 m0, s45
	s_nop 0
	global_load_lds_dwordx4 v172, s[98:99]
	s_waitcnt vmcnt(8)
	s_waitcnt lgkmcnt(0)
	s_barrier
	v_mfma_f32_16x16x128_f8f6f4 v[94:97], v[2:9], v[188:195], v[94:97]
	v_mfma_f32_16x16x128_f8f6f4 v[90:93], v[10:17], v[188:195], v[90:93]
	v_mfma_f32_16x16x128_f8f6f4 v[78:81], v[2:9], v[196:203], v[78:81]
	v_mfma_f32_16x16x128_f8f6f4 v[74:77], v[10:17], v[196:203], v[74:77]
	v_mfma_f32_16x16x128_f8f6f4 v[62:65], v[2:9], v[204:211], v[62:65]
	v_mfma_f32_16x16x128_f8f6f4 v[58:61], v[10:17], v[204:211], v[58:61]
	v_mfma_f32_16x16x128_f8f6f4 v[46:49], v[2:9], v[212:219], v[46:49]
	v_mfma_f32_16x16x128_f8f6f4 v[42:45], v[10:17], v[212:219], v[42:45]
	v_mfma_f32_16x16x128_f8f6f4 v[86:89], v[18:25], v[188:195], v[86:89]
	v_mfma_f32_16x16x128_f8f6f4 v[82:85], v[26:33], v[188:195], v[82:85]
	v_mfma_f32_16x16x128_f8f6f4 v[70:73], v[18:25], v[196:203], v[70:73]
	v_mfma_f32_16x16x128_f8f6f4 v[66:69], v[26:33], v[196:203], v[66:69]
	v_mfma_f32_16x16x128_f8f6f4 v[54:57], v[18:25], v[204:211], v[54:57]
	v_mfma_f32_16x16x128_f8f6f4 v[50:53], v[26:33], v[204:211], v[50:53]
	v_mfma_f32_16x16x128_f8f6f4 v[38:41], v[18:25], v[212:219], v[38:41]
	v_mfma_f32_16x16x128_f8f6f4 v[34:37], v[26:33], v[212:219], v[34:37]
	s_barrier
	s_add_i32 s29, s29, 2
	s_add_u32 s20, s20, 0x100
	s_addc_u32 s21, s21, 0
	s_add_u32 s27, s27, 0x100
	s_addc_u32 s28, s28, 0
	s_cmp_gt_u32 s29, 29
	s_cbranch_scc0 .LBB0_271
	s_and_b64 vcc, exec, s[8:9]
	s_cbranch_vccz .LBB0_274
	s_barrier

.LBB0_829:
	s_lshl_b32 s41, s8, 6
	s_lshl_b32 s11, s8, 13
	s_lshl_b32 s3, s3, 5
	s_mov_b64 s[8:9], 0x80
	s_and_b32 s42, s3, 0x60
	s_add_i32 m0, s27, 0x18000
	v_lshl_add_u64 v[8:9], v[8:9], 0, s[8:9]
	s_lshr_b32 s3, s42, 3
	s_waitcnt vmcnt(2)
	s_barrier
	global_load_lds_dwordx4 v[8:9], off
	v_lshl_add_u64 v[6:7], v[6:7], 0, s[8:9]
	s_add_i32 m0, s27, 0x1a000
	s_add_i32 s43, s27, 0x8000
	s_add_i32 s44, s27, 0xa000
	global_load_lds_dwordx4 v[6:7], off
	v_lshl_add_u64 v[2:3], v[2:3], 0, s[8:9]
	s_mov_b32 m0, s43
	s_add_u32 s14, s30, 0x40080
	global_load_lds_dwordx4 v[2:3], off
	v_lshl_add_u64 v[2:3], v[4:5], 0, s[8:9]
	s_mov_b32 m0, s44
	s_addc_u32 s15, s31, 0
	global_load_lds_dwordx4 v[2:3], off
	s_add_i32 m0, s27, 0x1c000
	v_lshl_add_u64 v[2:3], s[14:15], 0, v[168:169]
	global_load_lds_dwordx4 v[2:3], off
	v_lshl_add_u64 v[2:3], s[14:15], 0, v[170:171]
	s_add_i32 m0, s27, 0x1e000
	v_lshlrev_b32_e32 v4, 6, v10
	global_load_lds_dwordx4 v[2:3], off
	v_bfe_u32 v2, v10, 5, 1
	v_lshlrev_b32_e32 v3, 1, v10
	v_lshlrev_b32_e32 v7, 2, v10
	v_and_b32_e32 v3, 32, v3
	v_and_b32_e32 v4, 0x3c0, v4
	v_lshlrev_b32_e32 v6, 10, v2
	v_and_b32_e32 v7, 32, v7
	v_or_b32_e32 v2, s3, v2
	v_or_b32_e32 v5, v4, v3
	v_bitop3_b32 v3, v4, v7, v3 bitop3:0x36
	v_lshlrev_b32_e32 v2, 10, v2
	s_waitcnt vmcnt(6)
	s_cmpk_lt_u32 s10, 0x100
	v_or3_b32 v3, s11, v6, v3
	v_bitop3_b32 v182, v2, v5, v7 bitop3:0xf6
	s_cselect_b64 s[10:11], -1, 0
	s_add_i32 s46, 0, 0x10000
	s_add_i32 s47, 0, 0x14000
	s_sext_i32_i8 s48, s2
	s_ashr_i32 s45, s88, 31
	v_mov_b64_e32 v[164:165], 0x400
	v_mov_b64_e32 v[166:167], 0x3ff
	v_and_b32_e32 v250, 15, v0
	v_lshlrev_b32_e32 v250, 6, v250
	v_bfe_u32 v251, v0, 4, 1
	v_lshl_or_b32 v250, v251, 4, v250
	v_lshrrev_b32_e32 v251, 5, v0
	v_lshrrev_b32_e32 v252, 3, v0
	v_xor_b32_e32 v251, v251, v252
	v_and_b32_e32 v251, 1, v251
	v_lshl_or_b32 v250, v251, 5, v250
	v_and_b32_e32 v182, 0xf000, v182
	v_or_b32_e32 v182, v182, v250
	v_and_b32_e32 v3, 0xf000, v3
	v_or_b32_e32 v3, v3, v250
	v_add_u32_e32 v183, s46, v182
	v_add_u32_e32 v184, s47, v182
	v_add_u32_e32 v185, 0, v3
	v_mov_b32_e32 v186, 0x7f7f7f7f
	s_mov_b32 s12, 0x3c800000
	s_mov_b64 s[14:15], 0x140000
	s_mov_b64 s[16:17], 0x160000
	s_barrier
	s_branch .LBB0_832

.LBB0_838:
	s_ashr_i32 s21, s20, 31
	s_lshl_b64 s[22:23], s[20:21], 19
	s_add_u32 s22, s68, s22
	s_addc_u32 s23, s69, s23
	s_and_b64 s[24:25], s[2:3], exec
	s_cselect_b32 s21, s23, s29
	s_cselect_b32 s49, s22, s28
	s_ashr_i32 s19, s18, 31
	s_lshl_b64 s[24:25], s[18:19], 19
	v_readlane_b32 s34, v245, 14
	v_readlane_b32 s35, v245, 15
	s_add_u32 s24, s34, s24
	s_addc_u32 s25, s35, s25
	s_and_b64 s[34:35], s[2:3], exec
	s_cselect_b32 s19, s25, s31
	s_cselect_b32 s50, s24, s30
	s_add_u32 s28, s28, 0x40080
	s_addc_u32 s29, s29, 0
	s_add_u32 s51, s30, 0x100
	v_mov_b32_e32 v34, 0
	v_mov_b32_e32 v173, v163
	v_mov_b32_e32 v169, v163
	v_mov_b32_e32 v171, v163
	s_addc_u32 s52, s31, 0
	s_mov_b32 s53, -2
	v_mov_b32_e32 v35, v34
	v_mov_b32_e32 v36, v34
	v_mov_b32_e32 v37, v34
	v_mov_b32_e32 v38, v34
	v_mov_b32_e32 v39, v34
	v_mov_b32_e32 v40, v34
	v_mov_b32_e32 v41, v34
	v_mov_b32_e32 v50, v34
	v_mov_b32_e32 v51, v34
	v_mov_b32_e32 v52, v34
	v_mov_b32_e32 v53, v34
	v_mov_b32_e32 v54, v34
	v_mov_b32_e32 v55, v34
	v_mov_b32_e32 v56, v34
	v_mov_b32_e32 v57, v34
	v_mov_b32_e32 v66, v34
	v_mov_b32_e32 v67, v34
	v_mov_b32_e32 v68, v34
	v_mov_b32_e32 v69, v34
	v_mov_b32_e32 v70, v34
	v_mov_b32_e32 v71, v34
	v_mov_b32_e32 v72, v34
	v_mov_b32_e32 v73, v34
	v_mov_b32_e32 v82, v34
	v_mov_b32_e32 v83, v34
	v_mov_b32_e32 v84, v34
	v_mov_b32_e32 v85, v34
	v_mov_b32_e32 v86, v34
	v_mov_b32_e32 v87, v34
	v_mov_b32_e32 v88, v34
	v_mov_b32_e32 v89, v34
	v_mov_b32_e32 v42, v34
	v_mov_b32_e32 v43, v34
	v_mov_b32_e32 v44, v34
	v_mov_b32_e32 v45, v34
	v_mov_b32_e32 v46, v34
	v_mov_b32_e32 v47, v34
	v_mov_b32_e32 v48, v34
	v_mov_b32_e32 v49, v34
	v_mov_b32_e32 v58, v34
	v_mov_b32_e32 v59, v34
	v_mov_b32_e32 v60, v34
	v_mov_b32_e32 v61, v34
	v_mov_b32_e32 v62, v34
	v_mov_b32_e32 v63, v34
	v_mov_b32_e32 v64, v34
	v_mov_b32_e32 v65, v34
	v_mov_b32_e32 v74, v34
	v_mov_b32_e32 v75, v34
	v_mov_b32_e32 v76, v34
	v_mov_b32_e32 v77, v34
	v_mov_b32_e32 v78, v34
	v_mov_b32_e32 v79, v34
	v_mov_b32_e32 v80, v34
	v_mov_b32_e32 v81, v34
	v_mov_b32_e32 v90, v34
	v_mov_b32_e32 v91, v34
	v_mov_b32_e32 v92, v34
	v_mov_b32_e32 v93, v34
	v_mov_b32_e32 v94, v34
	v_mov_b32_e32 v95, v34
	v_mov_b32_e32 v96, v34
	v_mov_b32_e32 v97, v34
	s_waitcnt vmcnt(0)
	v_mov_b32_e32 v98, v34
	v_mov_b32_e32 v99, v34
	v_mov_b32_e32 v100, v34
	v_mov_b32_e32 v101, v34
	v_mov_b32_e32 v102, v34
	v_mov_b32_e32 v103, v34
	v_mov_b32_e32 v104, v34
	v_mov_b32_e32 v105, v34
	v_mov_b32_e32 v114, v34
	v_mov_b32_e32 v115, v34
	v_mov_b32_e32 v116, v34
	v_mov_b32_e32 v117, v34
	v_mov_b32_e32 v118, v34
	v_mov_b32_e32 v119, v34
	v_mov_b32_e32 v120, v34
	v_mov_b32_e32 v121, v34
	v_mov_b32_e32 v130, v34
	v_mov_b32_e32 v131, v34
	v_mov_b32_e32 v132, v34
	v_mov_b32_e32 v133, v34
	v_mov_b32_e32 v134, v34
	v_mov_b32_e32 v135, v34
	v_mov_b32_e32 v136, v34
	v_mov_b32_e32 v137, v34
	v_mov_b32_e32 v146, v34
	v_mov_b32_e32 v147, v34
	v_mov_b32_e32 v148, v34
	v_mov_b32_e32 v149, v34
	v_mov_b32_e32 v150, v34
	v_mov_b32_e32 v151, v34
	v_mov_b32_e32 v152, v34
	v_mov_b32_e32 v153, v34
	v_mov_b32_e32 v106, v34
	v_mov_b32_e32 v107, v34
	v_mov_b32_e32 v108, v34
	v_mov_b32_e32 v109, v34
	v_mov_b32_e32 v110, v34
	v_mov_b32_e32 v111, v34
	v_mov_b32_e32 v112, v34
	v_mov_b32_e32 v113, v34
	v_mov_b32_e32 v122, v34
	v_mov_b32_e32 v123, v34
	v_mov_b32_e32 v124, v34
	v_mov_b32_e32 v125, v34
	v_mov_b32_e32 v126, v34
	v_mov_b32_e32 v127, v34
	v_mov_b32_e32 v128, v34
	v_mov_b32_e32 v129, v34
	v_mov_b32_e32 v138, v34
	v_mov_b32_e32 v139, v34
	v_mov_b32_e32 v140, v34
	v_mov_b32_e32 v141, v34
	v_mov_b32_e32 v142, v34
	v_mov_b32_e32 v143, v34
	v_mov_b32_e32 v144, v34
	v_mov_b32_e32 v145, v34
	v_mov_b32_e32 v154, v34
	v_mov_b32_e32 v155, v34
	v_mov_b32_e32 v156, v34
	v_mov_b32_e32 v157, v34
	v_mov_b32_e32 v158, v34
	v_mov_b32_e32 v159, v34
	v_mov_b32_e32 v160, v34
	v_mov_b32_e32 v161, v34
	v_add_u32_e32 v246, 0x18000, v182
	v_add_u32_e32 v247, 0x1c000, v182
.LBB0_839:
	ds_read_b128 v[26:29], v183
	ds_read_b128 v[30:33], v183 offset:1024
	ds_read_b128 v[18:21], v183 offset:2048
	ds_read_b128 v[22:25], v183 offset:3072
	ds_read_b128 v[10:13], v184
	ds_read_b128 v[14:17], v184 offset:1024
	ds_read_b128 v[2:5], v184 offset:2048
	ds_read_b128 v[6:9], v184 offset:3072
	s_add_u32 s30, s28, 0xfffc0080
	s_addc_u32 s31, s29, -1
	s_cmp_eq_u32 s53, 12
	s_cselect_b32 s35, s21, s31
	s_cselect_b32 s34, s49, s30
	s_cselect_b32 s31, s19, s52
	s_cselect_b32 s30, s50, s51
	s_add_i32 m0, s27, 0xc000
	ds_read_b128 v[174:177], v185
	ds_read_b128 v[178:181], v185 offset:1024
	ds_read_b128 v[188:191], v185 offset:2048
	ds_read_b128 v[192:195], v185 offset:3072
	ds_read_b128 v[196:199], v185 offset:4096
	ds_read_b128 v[200:203], v185 offset:5120
	ds_read_b128 v[204:207], v185 offset:6144
	ds_read_b128 v[208:211], v185 offset:7168
	global_load_lds_dwordx4 v162, s[28:29]
	s_add_i32 m0, s27, 0xe000
	s_nop 0
	global_load_lds_dwordx4 v172, s[28:29]
	s_waitcnt vmcnt(8)
	s_waitcnt lgkmcnt(0)
	s_barrier
	v_mfma_f32_16x16x128_f8f6f4 v[158:161], v[26:33], v[174:181], v[158:161]
	v_mfma_f32_16x16x128_f8f6f4 v[154:157], v[18:25], v[174:181], v[154:157]
	v_mfma_f32_16x16x128_f8f6f4 v[142:145], v[26:33], v[188:195], v[142:145]
	v_mfma_f32_16x16x128_f8f6f4 v[138:141], v[18:25], v[188:195], v[138:141]
	v_mfma_f32_16x16x128_f8f6f4 v[126:129], v[26:33], v[196:203], v[126:129]
	v_mfma_f32_16x16x128_f8f6f4 v[122:125], v[18:25], v[196:203], v[122:125]
	v_mfma_f32_16x16x128_f8f6f4 v[110:113], v[26:33], v[204:211], v[110:113]
	v_mfma_f32_16x16x128_f8f6f4 v[106:109], v[18:25], v[204:211], v[106:109]
	v_mfma_f32_16x16x128_f8f6f4 v[150:153], v[10:17], v[174:181], v[150:153]
	v_mfma_f32_16x16x128_f8f6f4 v[146:149], v[2:9], v[174:181], v[146:149]
	v_mfma_f32_16x16x128_f8f6f4 v[134:137], v[10:17], v[188:195], v[134:137]
	v_mfma_f32_16x16x128_f8f6f4 v[130:133], v[2:9], v[188:195], v[130:133]
	v_mfma_f32_16x16x128_f8f6f4 v[118:121], v[10:17], v[196:203], v[118:121]
	v_mfma_f32_16x16x128_f8f6f4 v[114:117], v[2:9], v[196:203], v[114:117]
	v_mfma_f32_16x16x128_f8f6f4 v[102:105], v[10:17], v[204:211], v[102:105]
	v_mfma_f32_16x16x128_f8f6f4 v[98:101], v[2:9], v[204:211], v[98:101]
	s_barrier
	s_add_i32 s54, s46, s36
	s_mov_b32 m0, s54
	ds_read_b128 v[188:191], v185 offset:16384
	ds_read_b128 v[192:195], v185 offset:17408
	ds_read_b128 v[196:199], v185 offset:18432
	ds_read_b128 v[200:203], v185 offset:19456
	ds_read_b128 v[204:207], v185 offset:20480
	ds_read_b128 v[208:211], v185 offset:21504
	ds_read_b128 v[212:215], v185 offset:22528
	ds_read_b128 v[216:219], v185 offset:23552
	global_load_lds_dwordx4 v168, s[30:31]
	s_add_i32 m0, s54, 0x2000
	s_add_u32 s54, s30, 0x40000
	s_addc_u32 s55, s31, 0
	s_add_i32 s56, s47, s36
	global_load_lds_dwordx4 v170, s[30:31]
	s_mov_b32 m0, s56
	global_load_lds_dwordx4 v168, s[54:55]
	s_add_i32 m0, s56, 0x2000
	s_nop 0
	global_load_lds_dwordx4 v170, s[54:55]
	s_mov_b32 m0, s27
	s_nop 0
	global_load_lds_dwordx4 v162, s[34:35]
	s_mov_b32 m0, s37
	s_nop 0
	global_load_lds_dwordx4 v172, s[34:35]
	s_waitcnt vmcnt(8)
	s_waitcnt lgkmcnt(0)
	s_barrier
	v_mfma_f32_16x16x128_f8f6f4 v[94:97], v[26:33], v[188:195], v[94:97]
	v_mfma_f32_16x16x128_f8f6f4 v[90:93], v[18:25], v[188:195], v[90:93]
	v_mfma_f32_16x16x128_f8f6f4 v[78:81], v[26:33], v[196:203], v[78:81]
	v_mfma_f32_16x16x128_f8f6f4 v[74:77], v[18:25], v[196:203], v[74:77]
	v_mfma_f32_16x16x128_f8f6f4 v[62:65], v[26:33], v[204:211], v[62:65]
	v_mfma_f32_16x16x128_f8f6f4 v[58:61], v[18:25], v[204:211], v[58:61]
	v_mfma_f32_16x16x128_f8f6f4 v[46:49], v[26:33], v[212:219], v[46:49]
	v_mfma_f32_16x16x128_f8f6f4 v[42:45], v[18:25], v[212:219], v[42:45]
	v_mfma_f32_16x16x128_f8f6f4 v[86:89], v[10:17], v[188:195], v[86:89]
	v_mfma_f32_16x16x128_f8f6f4 v[82:85], v[2:9], v[188:195], v[82:85]
	v_mfma_f32_16x16x128_f8f6f4 v[70:73], v[10:17], v[196:203], v[70:73]
	v_mfma_f32_16x16x128_f8f6f4 v[66:69], v[2:9], v[196:203], v[66:69]
	v_mfma_f32_16x16x128_f8f6f4 v[54:57], v[10:17], v[204:211], v[54:57]
	v_mfma_f32_16x16x128_f8f6f4 v[50:53], v[2:9], v[204:211], v[50:53]
	v_mfma_f32_16x16x128_f8f6f4 v[38:41], v[10:17], v[212:219], v[38:41]
	v_mfma_f32_16x16x128_f8f6f4 v[34:37], v[2:9], v[212:219], v[34:37]
	s_barrier
	s_add_i32 s54, 0, 0x18000
	s_add_i32 s55, 0, 0x1c000
	ds_read_b128 v[2:5], v246
	ds_read_b128 v[6:9], v246 offset:1024
	ds_read_b128 v[10:13], v246 offset:2048
	ds_read_b128 v[14:17], v246 offset:3072
	ds_read_b128 v[18:21], v247
	ds_read_b128 v[22:25], v247 offset:1024
	ds_read_b128 v[26:29], v247 offset:2048
	ds_read_b128 v[30:33], v247 offset:3072
	s_add_u32 s98, s34, 0x80
	s_addc_u32 s99, s35, 0
	s_add_u32 s34, s34, 0x40000
	s_addc_u32 s35, s35, 0
	s_mov_b32 m0, s38
	ds_read_b128 v[188:191], v185 offset:32768
	ds_read_b128 v[192:195], v185 offset:33792
	ds_read_b128 v[196:199], v185 offset:34816
	ds_read_b128 v[200:203], v185 offset:35840
	ds_read_b128 v[204:207], v185 offset:36864
	ds_read_b128 v[208:211], v185 offset:37888
	ds_read_b128 v[212:215], v185 offset:38912
	ds_read_b128 v[216:219], v185 offset:39936
	global_load_lds_dwordx4 v162, s[34:35]
	s_mov_b32 m0, s39
	s_nop 0
	global_load_lds_dwordx4 v172, s[34:35]
	s_waitcnt vmcnt(8)
	s_waitcnt lgkmcnt(0)
	s_barrier
	v_mfma_f32_16x16x128_f8f6f4 v[158:161], v[2:9], v[188:195], v[158:161]
	v_mfma_f32_16x16x128_f8f6f4 v[154:157], v[10:17], v[188:195], v[154:157]
	v_mfma_f32_16x16x128_f8f6f4 v[142:145], v[2:9], v[196:203], v[142:145]
	v_mfma_f32_16x16x128_f8f6f4 v[138:141], v[10:17], v[196:203], v[138:141]
	v_mfma_f32_16x16x128_f8f6f4 v[126:129], v[2:9], v[204:211], v[126:129]
	v_mfma_f32_16x16x128_f8f6f4 v[122:125], v[10:17], v[204:211], v[122:125]
	v_mfma_f32_16x16x128_f8f6f4 v[110:113], v[2:9], v[212:219], v[110:113]
	v_mfma_f32_16x16x128_f8f6f4 v[106:109], v[10:17], v[212:219], v[106:109]
	v_mfma_f32_16x16x128_f8f6f4 v[150:153], v[18:25], v[188:195], v[150:153]
	v_mfma_f32_16x16x128_f8f6f4 v[146:149], v[26:33], v[188:195], v[146:149]
	v_mfma_f32_16x16x128_f8f6f4 v[134:137], v[18:25], v[196:203], v[134:137]
	v_mfma_f32_16x16x128_f8f6f4 v[130:133], v[26:33], v[196:203], v[130:133]
	v_mfma_f32_16x16x128_f8f6f4 v[118:121], v[18:25], v[204:211], v[118:121]
	v_mfma_f32_16x16x128_f8f6f4 v[114:117], v[26:33], v[204:211], v[114:117]
	v_mfma_f32_16x16x128_f8f6f4 v[102:105], v[18:25], v[212:219], v[102:105]
	v_mfma_f32_16x16x128_f8f6f4 v[98:101], v[26:33], v[212:219], v[98:101]
	s_barrier
	s_add_i32 s34, s54, s36
	s_mov_b32 m0, s34
	ds_read_b128 v[188:191], v185 offset:49152
	ds_read_b128 v[192:195], v185 offset:50176
	ds_read_b128 v[196:199], v185 offset:51200
	ds_read_b128 v[200:203], v185 offset:52224
	ds_read_b128 v[204:207], v185 offset:53248
	ds_read_b128 v[208:211], v185 offset:54272
	ds_read_b128 v[212:215], v185 offset:55296
	ds_read_b128 v[216:219], v185 offset:56320
	s_add_u32 s30, s30, 0x80
	s_addc_u32 s31, s31, 0
	global_load_lds_dwordx4 v168, s[30:31]
	s_add_i32 m0, s34, 0x2000
	s_add_i32 s34, s55, s36
	global_load_lds_dwordx4 v170, s[30:31]
	s_add_u32 s30, s30, 0x40000
	s_addc_u32 s31, s31, 0
	s_mov_b32 m0, s34
	s_nop 0
	global_load_lds_dwordx4 v168, s[30:31]
	s_add_i32 m0, s34, 0x2000
	s_nop 0
	global_load_lds_dwordx4 v170, s[30:31]
	s_mov_b32 m0, s43
	s_nop 0
	global_load_lds_dwordx4 v162, s[98:99]
	s_mov_b32 m0, s44
	s_nop 0
	global_load_lds_dwordx4 v172, s[98:99]
	s_waitcnt vmcnt(8)
	s_waitcnt lgkmcnt(0)
	s_barrier
	v_mfma_f32_16x16x128_f8f6f4 v[94:97], v[2:9], v[188:195], v[94:97]
	v_mfma_f32_16x16x128_f8f6f4 v[90:93], v[10:17], v[188:195], v[90:93]
	v_mfma_f32_16x16x128_f8f6f4 v[78:81], v[2:9], v[196:203], v[78:81]
	v_mfma_f32_16x16x128_f8f6f4 v[74:77], v[10:17], v[196:203], v[74:77]
	v_mfma_f32_16x16x128_f8f6f4 v[62:65], v[2:9], v[204:211], v[62:65]
	v_mfma_f32_16x16x128_f8f6f4 v[58:61], v[10:17], v[204:211], v[58:61]
	v_mfma_f32_16x16x128_f8f6f4 v[46:49], v[2:9], v[212:219], v[46:49]
	v_mfma_f32_16x16x128_f8f6f4 v[42:45], v[10:17], v[212:219], v[42:45]
	v_mfma_f32_16x16x128_f8f6f4 v[86:89], v[18:25], v[188:195], v[86:89]
	v_mfma_f32_16x16x128_f8f6f4 v[82:85], v[26:33], v[188:195], v[82:85]
	v_mfma_f32_16x16x128_f8f6f4 v[70:73], v[18:25], v[196:203], v[70:73]
	v_mfma_f32_16x16x128_f8f6f4 v[66:69], v[26:33], v[196:203], v[66:69]
	v_mfma_f32_16x16x128_f8f6f4 v[54:57], v[18:25], v[204:211], v[54:57]
	v_mfma_f32_16x16x128_f8f6f4 v[50:53], v[26:33], v[204:211], v[50:53]
	v_mfma_f32_16x16x128_f8f6f4 v[38:41], v[18:25], v[212:219], v[38:41]
	v_mfma_f32_16x16x128_f8f6f4 v[34:37], v[26:33], v[212:219], v[34:37]
	s_barrier
	s_add_i32 s53, s53, 2
	s_add_u32 s28, s28, 0x100
	s_addc_u32 s29, s29, 0
	s_add_u32 s51, s51, 0x100
	s_addc_u32 s52, s52, 0
	s_cmp_gt_u32 s53, 13
	s_cbranch_scc0 .LBB0_839
	s_and_b64 vcc, exec, s[10:11]
	s_cbranch_vccz .LBB0_842
	s_barrier

.LBB0_862:
	s_ashr_i32 s13, s12, 31
	s_lshl_b64 s[14:15], s[12:13], 20
	s_add_u32 s14, s62, s14
	s_addc_u32 s15, s63, s15
	s_and_b64 s[16:17], s[2:3], exec
	s_cselect_b32 s13, s15, s21
	s_cselect_b32 s39, s14, s20
	s_ashr_i32 s11, s10, 31
	s_lshl_b64 s[16:17], s[10:11], 20
	v_readlane_b32 s24, v245, 16
	v_readlane_b32 s25, v245, 17
	s_add_u32 s16, s24, s16
	s_addc_u32 s17, s25, s17
	s_and_b64 s[24:25], s[2:3], exec
	s_cselect_b32 s11, s17, s23
	s_cselect_b32 s40, s16, s22
	s_add_u32 s20, s20, 0x80080
	s_addc_u32 s21, s21, 0
	s_add_u32 s41, s22, 0x100
	v_mov_b32_e32 v2, 0
	s_addc_u32 s42, s23, 0
	s_mov_b32 s43, -2
	v_mov_b32_e32 v3, v2
	v_mov_b32_e32 v4, v2
	v_mov_b32_e32 v5, v2
	v_mov_b32_e32 v6, v2
	v_mov_b32_e32 v7, v2
	v_mov_b32_e32 v8, v2
	v_mov_b32_e32 v9, v2
	v_mov_b32_e32 v18, v2
	v_mov_b32_e32 v19, v2
	v_mov_b32_e32 v20, v2
	v_mov_b32_e32 v21, v2
	v_mov_b32_e32 v22, v2
	v_mov_b32_e32 v23, v2
	v_mov_b32_e32 v24, v2
	v_mov_b32_e32 v25, v2
	v_mov_b32_e32 v34, v2
	v_mov_b32_e32 v35, v2
	v_mov_b32_e32 v36, v2
	v_mov_b32_e32 v37, v2
	v_mov_b32_e32 v38, v2
	v_mov_b32_e32 v39, v2
	v_mov_b32_e32 v40, v2
	v_mov_b32_e32 v41, v2
	v_mov_b32_e32 v50, v2
	v_mov_b32_e32 v51, v2
	v_mov_b32_e32 v52, v2
	v_mov_b32_e32 v53, v2
	v_mov_b32_e32 v54, v2
	v_mov_b32_e32 v55, v2
	v_mov_b32_e32 v56, v2
	v_mov_b32_e32 v57, v2
	v_mov_b32_e32 v10, v2
	v_mov_b32_e32 v11, v2
	v_mov_b32_e32 v12, v2
	v_mov_b32_e32 v13, v2
	v_mov_b32_e32 v14, v2
	v_mov_b32_e32 v15, v2
	v_mov_b32_e32 v16, v2
	v_mov_b32_e32 v17, v2
	v_mov_b32_e32 v26, v2
	v_mov_b32_e32 v27, v2
	v_mov_b32_e32 v28, v2
	v_mov_b32_e32 v29, v2
	v_mov_b32_e32 v30, v2
	v_mov_b32_e32 v31, v2
	v_mov_b32_e32 v32, v2
	v_mov_b32_e32 v33, v2
	v_mov_b32_e32 v42, v2
	v_mov_b32_e32 v43, v2
	v_mov_b32_e32 v44, v2
	v_mov_b32_e32 v45, v2
	v_mov_b32_e32 v46, v2
	v_mov_b32_e32 v47, v2
	v_mov_b32_e32 v48, v2
	v_mov_b32_e32 v49, v2
	v_mov_b32_e32 v58, v2
	v_mov_b32_e32 v59, v2
	v_mov_b32_e32 v60, v2
	v_mov_b32_e32 v61, v2
	v_mov_b32_e32 v62, v2
	v_mov_b32_e32 v63, v2
	v_mov_b32_e32 v64, v2
	v_mov_b32_e32 v65, v2
	v_mov_b32_e32 v66, v2
	v_mov_b32_e32 v67, v2
	v_mov_b32_e32 v68, v2
	v_mov_b32_e32 v69, v2
	v_mov_b32_e32 v70, v2
	v_mov_b32_e32 v71, v2
	v_mov_b32_e32 v72, v2
	v_mov_b32_e32 v73, v2
	v_mov_b32_e32 v82, v2
	v_mov_b32_e32 v83, v2
	v_mov_b32_e32 v84, v2
	v_mov_b32_e32 v85, v2
	v_mov_b32_e32 v86, v2
	v_mov_b32_e32 v87, v2
	v_mov_b32_e32 v88, v2
	v_mov_b32_e32 v89, v2
	v_mov_b32_e32 v98, v2
	v_mov_b32_e32 v99, v2
	v_mov_b32_e32 v100, v2
	v_mov_b32_e32 v101, v2
	v_mov_b32_e32 v102, v2
	v_mov_b32_e32 v103, v2
	v_mov_b32_e32 v104, v2
	v_mov_b32_e32 v105, v2
	v_mov_b32_e32 v114, v2
	v_mov_b32_e32 v115, v2
	v_mov_b32_e32 v116, v2
	v_mov_b32_e32 v117, v2
	v_mov_b32_e32 v118, v2
	v_mov_b32_e32 v119, v2
	v_mov_b32_e32 v120, v2
	v_mov_b32_e32 v121, v2
	v_mov_b32_e32 v74, v2
	v_mov_b32_e32 v75, v2
	v_mov_b32_e32 v76, v2
	v_mov_b32_e32 v77, v2
	v_mov_b32_e32 v78, v2
	v_mov_b32_e32 v79, v2
	v_mov_b32_e32 v80, v2
	v_mov_b32_e32 v81, v2
	v_mov_b32_e32 v90, v2
	v_mov_b32_e32 v91, v2
	v_mov_b32_e32 v92, v2
	v_mov_b32_e32 v93, v2
	v_mov_b32_e32 v94, v2
	v_mov_b32_e32 v95, v2
	v_mov_b32_e32 v96, v2
	v_mov_b32_e32 v97, v2
	v_mov_b32_e32 v106, v2
	v_mov_b32_e32 v107, v2
	v_mov_b32_e32 v108, v2
	v_mov_b32_e32 v109, v2
	v_mov_b32_e32 v110, v2
	v_mov_b32_e32 v111, v2
	v_mov_b32_e32 v112, v2
	v_mov_b32_e32 v113, v2
	v_mov_b32_e32 v122, v2
	v_mov_b32_e32 v123, v2
	v_mov_b32_e32 v124, v2
	v_mov_b32_e32 v125, v2
	v_mov_b32_e32 v126, v2
	v_mov_b32_e32 v127, v2
	v_mov_b32_e32 v128, v2
	v_mov_b32_e32 v129, v2
	v_add_u32_e32 v246, 0x18000, v152
	v_add_u32_e32 v247, 0x1c000, v152
.LBB0_863:
	ds_read_b128 v[146:149], v154
	ds_read_b128 v[158:161], v154 offset:1024
	ds_read_b128 v[162:165], v154 offset:2048
	ds_read_b128 v[166:169], v154 offset:3072
	ds_read_b128 v[170:173], v155
	ds_read_b128 v[174:177], v155 offset:1024
	ds_read_b128 v[178:181], v155 offset:2048
	ds_read_b128 v[182:185], v155 offset:3072
	s_add_u32 s22, s20, 0xfff80080
	s_addc_u32 s23, s21, -1
	s_cmp_eq_u32 s43, 28
	s_cselect_b32 s25, s13, s23
	s_cselect_b32 s24, s39, s22
	s_cselect_b32 s23, s11, s42
	s_cselect_b32 s22, s40, s41
	s_add_i32 m0, s19, 0xc000
	ds_read_b128 v[186:189], v156
	ds_read_b128 v[190:193], v156 offset:1024
	ds_read_b128 v[194:197], v156 offset:2048
	ds_read_b128 v[198:201], v156 offset:3072
	ds_read_b128 v[202:205], v156 offset:4096
	ds_read_b128 v[206:209], v156 offset:5120
	ds_read_b128 v[210:213], v156 offset:6144
	ds_read_b128 v[214:217], v156 offset:7168
	global_load_lds_dwordx4 v138, s[20:21]
	s_add_i32 m0, s19, 0xe000
	s_nop 0
	global_load_lds_dwordx4 v140, s[20:21]
	s_waitcnt vmcnt(8)
	s_waitcnt lgkmcnt(0)
	s_barrier
	v_mfma_f32_16x16x32_bf16 v[126:129], v[146:149], v[186:189], v[126:129]
	v_mfma_f32_16x16x32_bf16 v[126:129], v[158:161], v[190:193], v[126:129]
	v_mfma_f32_16x16x32_bf16 v[122:125], v[162:165], v[186:189], v[122:125]
	v_mfma_f32_16x16x32_bf16 v[122:125], v[166:169], v[190:193], v[122:125]
	v_mfma_f32_16x16x32_bf16 v[110:113], v[146:149], v[194:197], v[110:113]
	v_mfma_f32_16x16x32_bf16 v[110:113], v[158:161], v[198:201], v[110:113]
	v_mfma_f32_16x16x32_bf16 v[106:109], v[162:165], v[194:197], v[106:109]
	v_mfma_f32_16x16x32_bf16 v[106:109], v[166:169], v[198:201], v[106:109]
	v_mfma_f32_16x16x32_bf16 v[94:97], v[146:149], v[202:205], v[94:97]
	v_mfma_f32_16x16x32_bf16 v[94:97], v[158:161], v[206:209], v[94:97]
	v_mfma_f32_16x16x32_bf16 v[90:93], v[162:165], v[202:205], v[90:93]
	v_mfma_f32_16x16x32_bf16 v[90:93], v[166:169], v[206:209], v[90:93]
	v_mfma_f32_16x16x32_bf16 v[78:81], v[146:149], v[210:213], v[78:81]
	v_mfma_f32_16x16x32_bf16 v[78:81], v[158:161], v[214:217], v[78:81]
	v_mfma_f32_16x16x32_bf16 v[74:77], v[162:165], v[210:213], v[74:77]
	v_mfma_f32_16x16x32_bf16 v[74:77], v[166:169], v[214:217], v[74:77]
	v_mfma_f32_16x16x32_bf16 v[118:121], v[170:173], v[186:189], v[118:121]
	v_mfma_f32_16x16x32_bf16 v[118:121], v[174:177], v[190:193], v[118:121]
	v_mfma_f32_16x16x32_bf16 v[114:117], v[178:181], v[186:189], v[114:117]
	v_mfma_f32_16x16x32_bf16 v[114:117], v[182:185], v[190:193], v[114:117]
	v_mfma_f32_16x16x32_bf16 v[102:105], v[170:173], v[194:197], v[102:105]
	v_mfma_f32_16x16x32_bf16 v[102:105], v[174:177], v[198:201], v[102:105]
	v_mfma_f32_16x16x32_bf16 v[98:101], v[178:181], v[194:197], v[98:101]
	v_mfma_f32_16x16x32_bf16 v[98:101], v[182:185], v[198:201], v[98:101]
	v_mfma_f32_16x16x32_bf16 v[86:89], v[170:173], v[202:205], v[86:89]
	v_mfma_f32_16x16x32_bf16 v[86:89], v[174:177], v[206:209], v[86:89]
	v_mfma_f32_16x16x32_bf16 v[82:85], v[178:181], v[202:205], v[82:85]
	v_mfma_f32_16x16x32_bf16 v[82:85], v[182:185], v[206:209], v[82:85]
	v_mfma_f32_16x16x32_bf16 v[70:73], v[170:173], v[210:213], v[70:73]
	v_mfma_f32_16x16x32_bf16 v[70:73], v[174:177], v[214:217], v[70:73]
	v_mfma_f32_16x16x32_bf16 v[66:69], v[178:181], v[210:213], v[66:69]
	v_mfma_f32_16x16x32_bf16 v[66:69], v[182:185], v[214:217], v[66:69]
	s_barrier
	s_add_i32 s44, s36, s27
	s_mov_b32 m0, s44
	ds_read_b128 v[186:189], v156 offset:16384
	ds_read_b128 v[190:193], v156 offset:17408
	ds_read_b128 v[194:197], v156 offset:18432
	ds_read_b128 v[198:201], v156 offset:19456
	ds_read_b128 v[202:205], v156 offset:20480
	ds_read_b128 v[206:209], v156 offset:21504
	ds_read_b128 v[210:213], v156 offset:22528
	ds_read_b128 v[214:217], v156 offset:23552
	global_load_lds_dwordx4 v132, s[22:23]
	s_add_i32 m0, s44, 0x2000
	s_add_u32 s44, s22, 0x80000
	s_addc_u32 s45, s23, 0
	s_add_i32 s46, s37, s27
	global_load_lds_dwordx4 v136, s[22:23]
	s_mov_b32 m0, s46
	global_load_lds_dwordx4 v132, s[44:45]
	s_add_i32 m0, s46, 0x2000
	s_nop 0
	global_load_lds_dwordx4 v136, s[44:45]
	s_mov_b32 m0, s19
	s_nop 0
	global_load_lds_dwordx4 v130, s[24:25]
	s_mov_b32 m0, s28
	s_nop 0
	global_load_lds_dwordx4 v134, s[24:25]
	s_waitcnt vmcnt(8)
	s_waitcnt lgkmcnt(0)
	s_barrier
	v_mfma_f32_16x16x32_bf16 v[62:65], v[146:149], v[186:189], v[62:65]
	v_mfma_f32_16x16x32_bf16 v[62:65], v[158:161], v[190:193], v[62:65]
	v_mfma_f32_16x16x32_bf16 v[58:61], v[162:165], v[186:189], v[58:61]
	v_mfma_f32_16x16x32_bf16 v[58:61], v[166:169], v[190:193], v[58:61]
	v_mfma_f32_16x16x32_bf16 v[46:49], v[146:149], v[194:197], v[46:49]
	v_mfma_f32_16x16x32_bf16 v[46:49], v[158:161], v[198:201], v[46:49]
	v_mfma_f32_16x16x32_bf16 v[42:45], v[162:165], v[194:197], v[42:45]
	v_mfma_f32_16x16x32_bf16 v[42:45], v[166:169], v[198:201], v[42:45]
	v_mfma_f32_16x16x32_bf16 v[30:33], v[146:149], v[202:205], v[30:33]
	v_mfma_f32_16x16x32_bf16 v[30:33], v[158:161], v[206:209], v[30:33]
	v_mfma_f32_16x16x32_bf16 v[26:29], v[162:165], v[202:205], v[26:29]
	v_mfma_f32_16x16x32_bf16 v[26:29], v[166:169], v[206:209], v[26:29]
	v_mfma_f32_16x16x32_bf16 v[14:17], v[146:149], v[210:213], v[14:17]
	v_mfma_f32_16x16x32_bf16 v[14:17], v[158:161], v[214:217], v[14:17]
	v_mfma_f32_16x16x32_bf16 v[10:13], v[162:165], v[210:213], v[10:13]
	v_mfma_f32_16x16x32_bf16 v[10:13], v[166:169], v[214:217], v[10:13]
	v_mfma_f32_16x16x32_bf16 v[54:57], v[170:173], v[186:189], v[54:57]
	v_mfma_f32_16x16x32_bf16 v[54:57], v[174:177], v[190:193], v[54:57]
	v_mfma_f32_16x16x32_bf16 v[50:53], v[178:181], v[186:189], v[50:53]
	v_mfma_f32_16x16x32_bf16 v[50:53], v[182:185], v[190:193], v[50:53]
	v_mfma_f32_16x16x32_bf16 v[38:41], v[170:173], v[194:197], v[38:41]
	v_mfma_f32_16x16x32_bf16 v[38:41], v[174:177], v[198:201], v[38:41]
	v_mfma_f32_16x16x32_bf16 v[34:37], v[178:181], v[194:197], v[34:37]
	v_mfma_f32_16x16x32_bf16 v[34:37], v[182:185], v[198:201], v[34:37]
	v_mfma_f32_16x16x32_bf16 v[22:25], v[170:173], v[202:205], v[22:25]
	v_mfma_f32_16x16x32_bf16 v[22:25], v[174:177], v[206:209], v[22:25]
	v_mfma_f32_16x16x32_bf16 v[18:21], v[178:181], v[202:205], v[18:21]
	v_mfma_f32_16x16x32_bf16 v[18:21], v[182:185], v[206:209], v[18:21]
	v_mfma_f32_16x16x32_bf16 v[6:9], v[170:173], v[210:213], v[6:9]
	v_mfma_f32_16x16x32_bf16 v[6:9], v[174:177], v[214:217], v[6:9]
	v_mfma_f32_16x16x32_bf16 v[2:5], v[178:181], v[210:213], v[2:5]
	v_mfma_f32_16x16x32_bf16 v[2:5], v[182:185], v[214:217], v[2:5]
	s_barrier
	s_add_i32 s44, 0, 0x18000
	s_add_i32 s45, 0, 0x1c000
	ds_read_b128 v[146:149], v246
	ds_read_b128 v[158:161], v246 offset:1024
	ds_read_b128 v[162:165], v246 offset:2048
	ds_read_b128 v[166:169], v246 offset:3072
	ds_read_b128 v[170:173], v247
	ds_read_b128 v[174:177], v247 offset:1024
	ds_read_b128 v[178:181], v247 offset:2048
	ds_read_b128 v[182:185], v247 offset:3072
	s_add_u32 s98, s24, 0x80
	s_addc_u32 s99, s25, 0
	s_add_u32 s24, s24, 0x80000
	s_addc_u32 s25, s25, 0
	s_mov_b32 m0, s29
	ds_read_b128 v[186:189], v156 offset:32768
	ds_read_b128 v[190:193], v156 offset:33792
	ds_read_b128 v[194:197], v156 offset:34816
	ds_read_b128 v[198:201], v156 offset:35840
	ds_read_b128 v[202:205], v156 offset:36864
	ds_read_b128 v[206:209], v156 offset:37888
	ds_read_b128 v[210:213], v156 offset:38912
	ds_read_b128 v[214:217], v156 offset:39936
	global_load_lds_dwordx4 v130, s[24:25]
	s_mov_b32 m0, s30
	s_nop 0
	global_load_lds_dwordx4 v134, s[24:25]
	s_waitcnt vmcnt(8)
	s_waitcnt lgkmcnt(0)
	s_barrier
	v_mfma_f32_16x16x32_bf16 v[126:129], v[146:149], v[186:189], v[126:129]
	v_mfma_f32_16x16x32_bf16 v[126:129], v[158:161], v[190:193], v[126:129]
	v_mfma_f32_16x16x32_bf16 v[122:125], v[162:165], v[186:189], v[122:125]
	v_mfma_f32_16x16x32_bf16 v[122:125], v[166:169], v[190:193], v[122:125]
	v_mfma_f32_16x16x32_bf16 v[110:113], v[146:149], v[194:197], v[110:113]
	v_mfma_f32_16x16x32_bf16 v[110:113], v[158:161], v[198:201], v[110:113]
	v_mfma_f32_16x16x32_bf16 v[106:109], v[162:165], v[194:197], v[106:109]
	v_mfma_f32_16x16x32_bf16 v[106:109], v[166:169], v[198:201], v[106:109]
	v_mfma_f32_16x16x32_bf16 v[94:97], v[146:149], v[202:205], v[94:97]
	v_mfma_f32_16x16x32_bf16 v[94:97], v[158:161], v[206:209], v[94:97]
	v_mfma_f32_16x16x32_bf16 v[90:93], v[162:165], v[202:205], v[90:93]
	v_mfma_f32_16x16x32_bf16 v[90:93], v[166:169], v[206:209], v[90:93]
	v_mfma_f32_16x16x32_bf16 v[78:81], v[146:149], v[210:213], v[78:81]
	v_mfma_f32_16x16x32_bf16 v[78:81], v[158:161], v[214:217], v[78:81]
	v_mfma_f32_16x16x32_bf16 v[74:77], v[162:165], v[210:213], v[74:77]
	v_mfma_f32_16x16x32_bf16 v[74:77], v[166:169], v[214:217], v[74:77]
	v_mfma_f32_16x16x32_bf16 v[118:121], v[170:173], v[186:189], v[118:121]
	v_mfma_f32_16x16x32_bf16 v[118:121], v[174:177], v[190:193], v[118:121]
	v_mfma_f32_16x16x32_bf16 v[114:117], v[178:181], v[186:189], v[114:117]
	v_mfma_f32_16x16x32_bf16 v[114:117], v[182:185], v[190:193], v[114:117]
	v_mfma_f32_16x16x32_bf16 v[102:105], v[170:173], v[194:197], v[102:105]
	v_mfma_f32_16x16x32_bf16 v[102:105], v[174:177], v[198:201], v[102:105]
	v_mfma_f32_16x16x32_bf16 v[98:101], v[178:181], v[194:197], v[98:101]
	v_mfma_f32_16x16x32_bf16 v[98:101], v[182:185], v[198:201], v[98:101]
	v_mfma_f32_16x16x32_bf16 v[86:89], v[170:173], v[202:205], v[86:89]
	v_mfma_f32_16x16x32_bf16 v[86:89], v[174:177], v[206:209], v[86:89]
	v_mfma_f32_16x16x32_bf16 v[82:85], v[178:181], v[202:205], v[82:85]
	v_mfma_f32_16x16x32_bf16 v[82:85], v[182:185], v[206:209], v[82:85]
	v_mfma_f32_16x16x32_bf16 v[70:73], v[170:173], v[210:213], v[70:73]
	v_mfma_f32_16x16x32_bf16 v[70:73], v[174:177], v[214:217], v[70:73]
	v_mfma_f32_16x16x32_bf16 v[66:69], v[178:181], v[210:213], v[66:69]
	v_mfma_f32_16x16x32_bf16 v[66:69], v[182:185], v[214:217], v[66:69]
	s_barrier
	s_add_i32 s24, s44, s27
	s_mov_b32 m0, s24
	ds_read_b128 v[186:189], v156 offset:49152
	ds_read_b128 v[190:193], v156 offset:50176
	ds_read_b128 v[194:197], v156 offset:51200
	ds_read_b128 v[198:201], v156 offset:52224
	ds_read_b128 v[202:205], v156 offset:53248
	ds_read_b128 v[206:209], v156 offset:54272
	ds_read_b128 v[210:213], v156 offset:55296
	ds_read_b128 v[214:217], v156 offset:56320
	s_add_u32 s22, s22, 0x80
	s_addc_u32 s23, s23, 0
	global_load_lds_dwordx4 v132, s[22:23]
	s_add_i32 m0, s24, 0x2000
	s_add_i32 s24, s45, s27
	global_load_lds_dwordx4 v136, s[22:23]
	s_add_u32 s22, s22, 0x80000
	s_addc_u32 s23, s23, 0
	s_mov_b32 m0, s24
	s_nop 0
	global_load_lds_dwordx4 v132, s[22:23]
	s_add_i32 m0, s24, 0x2000
	s_nop 0
	global_load_lds_dwordx4 v136, s[22:23]
	s_mov_b32 m0, s33
	s_nop 0
	global_load_lds_dwordx4 v130, s[98:99]
	s_mov_b32 m0, s34
	s_nop 0
	global_load_lds_dwordx4 v134, s[98:99]
	s_waitcnt vmcnt(8)
	s_waitcnt lgkmcnt(0)
	s_barrier
	v_mfma_f32_16x16x32_bf16 v[62:65], v[146:149], v[186:189], v[62:65]
	v_mfma_f32_16x16x32_bf16 v[62:65], v[158:161], v[190:193], v[62:65]
	v_mfma_f32_16x16x32_bf16 v[58:61], v[162:165], v[186:189], v[58:61]
	v_mfma_f32_16x16x32_bf16 v[58:61], v[166:169], v[190:193], v[58:61]
	v_mfma_f32_16x16x32_bf16 v[46:49], v[146:149], v[194:197], v[46:49]
	v_mfma_f32_16x16x32_bf16 v[46:49], v[158:161], v[198:201], v[46:49]
	v_mfma_f32_16x16x32_bf16 v[42:45], v[162:165], v[194:197], v[42:45]
	v_mfma_f32_16x16x32_bf16 v[42:45], v[166:169], v[198:201], v[42:45]
	v_mfma_f32_16x16x32_bf16 v[30:33], v[146:149], v[202:205], v[30:33]
	v_mfma_f32_16x16x32_bf16 v[30:33], v[158:161], v[206:209], v[30:33]
	v_mfma_f32_16x16x32_bf16 v[26:29], v[162:165], v[202:205], v[26:29]
	v_mfma_f32_16x16x32_bf16 v[26:29], v[166:169], v[206:209], v[26:29]
	v_mfma_f32_16x16x32_bf16 v[14:17], v[146:149], v[210:213], v[14:17]
	v_mfma_f32_16x16x32_bf16 v[14:17], v[158:161], v[214:217], v[14:17]
	v_mfma_f32_16x16x32_bf16 v[10:13], v[162:165], v[210:213], v[10:13]
	v_mfma_f32_16x16x32_bf16 v[10:13], v[166:169], v[214:217], v[10:13]
	v_mfma_f32_16x16x32_bf16 v[54:57], v[170:173], v[186:189], v[54:57]
	v_mfma_f32_16x16x32_bf16 v[54:57], v[174:177], v[190:193], v[54:57]
	v_mfma_f32_16x16x32_bf16 v[50:53], v[178:181], v[186:189], v[50:53]
	v_mfma_f32_16x16x32_bf16 v[50:53], v[182:185], v[190:193], v[50:53]
	v_mfma_f32_16x16x32_bf16 v[38:41], v[170:173], v[194:197], v[38:41]
	v_mfma_f32_16x16x32_bf16 v[38:41], v[174:177], v[198:201], v[38:41]
	v_mfma_f32_16x16x32_bf16 v[34:37], v[178:181], v[194:197], v[34:37]
	v_mfma_f32_16x16x32_bf16 v[34:37], v[182:185], v[198:201], v[34:37]
	v_mfma_f32_16x16x32_bf16 v[22:25], v[170:173], v[202:205], v[22:25]
	v_mfma_f32_16x16x32_bf16 v[22:25], v[174:177], v[206:209], v[22:25]
	v_mfma_f32_16x16x32_bf16 v[18:21], v[178:181], v[202:205], v[18:21]
	v_mfma_f32_16x16x32_bf16 v[18:21], v[182:185], v[206:209], v[18:21]
	v_mfma_f32_16x16x32_bf16 v[6:9], v[170:173], v[210:213], v[6:9]
	v_mfma_f32_16x16x32_bf16 v[6:9], v[174:177], v[214:217], v[6:9]
	v_mfma_f32_16x16x32_bf16 v[2:5], v[178:181], v[210:213], v[2:5]
	v_mfma_f32_16x16x32_bf16 v[2:5], v[182:185], v[214:217], v[2:5]
	s_barrier
	s_add_i32 s43, s43, 2
	s_add_u32 s20, s20, 0x100
	s_addc_u32 s21, s21, 0
	s_add_u32 s41, s41, 0x100
	s_addc_u32 s42, s42, 0
	s_cmp_gt_u32 s43, 29
	s_cbranch_scc0 .LBB0_863
	s_and_b64 vcc, exec, s[8:9]
	s_cbranch_vccz .LBB0_866
	s_barrier

.LBB0_940:
	s_ashr_i32 s21, s20, 31
	s_lshl_b64 s[22:23], s[20:21], 21
	s_add_u32 s22, s0, s22
	s_addc_u32 s23, s1, s23
	s_and_b64 s[24:25], s[4:5], exec
	s_cselect_b32 s21, s23, s29
	s_cselect_b32 s27, s22, s28
	s_ashr_i32 s19, s18, 31
	s_lshl_b64 s[24:25], s[18:19], 21
	v_readlane_b32 s34, v245, 18
	v_readlane_b32 s35, v245, 19
	s_add_u32 s24, s34, s24
	s_addc_u32 s25, s35, s25
	s_and_b64 s[34:35], s[4:5], exec
	s_cselect_b32 s19, s25, s31
	s_cselect_b32 s48, s24, s30
	s_add_u32 s28, s28, 0x100080
	s_addc_u32 s29, s29, 0
	s_add_u32 s49, s30, 0x100
	v_mov_b32_e32 v2, 0
	s_addc_u32 s50, s31, 0
	s_mov_b32 s51, -2
	s_waitcnt lgkmcnt(0)
	v_mov_b32_e32 v3, v2
	v_mov_b32_e32 v4, v2
	v_mov_b32_e32 v5, v2
	v_mov_b32_e32 v6, v2
	v_mov_b32_e32 v7, v2
	v_mov_b32_e32 v8, v2
	v_mov_b32_e32 v9, v2
	v_mov_b32_e32 v18, v2
	v_mov_b32_e32 v19, v2
	v_mov_b32_e32 v20, v2
	v_mov_b32_e32 v21, v2
	v_mov_b32_e32 v22, v2
	v_mov_b32_e32 v23, v2
	v_mov_b32_e32 v24, v2
	v_mov_b32_e32 v25, v2
	v_mov_b32_e32 v34, v2
	v_mov_b32_e32 v35, v2
	v_mov_b32_e32 v36, v2
	v_mov_b32_e32 v37, v2
	v_mov_b32_e32 v38, v2
	v_mov_b32_e32 v39, v2
	v_mov_b32_e32 v40, v2
	v_mov_b32_e32 v41, v2
	v_mov_b32_e32 v50, v2
	v_mov_b32_e32 v51, v2
	v_mov_b32_e32 v52, v2
	v_mov_b32_e32 v53, v2
	v_mov_b32_e32 v54, v2
	v_mov_b32_e32 v55, v2
	v_mov_b32_e32 v56, v2
	v_mov_b32_e32 v57, v2
	v_mov_b32_e32 v10, v2
	v_mov_b32_e32 v11, v2
	v_mov_b32_e32 v12, v2
	v_mov_b32_e32 v13, v2
	v_mov_b32_e32 v14, v2
	v_mov_b32_e32 v15, v2
	v_mov_b32_e32 v16, v2
	v_mov_b32_e32 v17, v2
	v_mov_b32_e32 v26, v2
	v_mov_b32_e32 v27, v2
	v_mov_b32_e32 v28, v2
	v_mov_b32_e32 v29, v2
	v_mov_b32_e32 v30, v2
	v_mov_b32_e32 v31, v2
	v_mov_b32_e32 v32, v2
	v_mov_b32_e32 v33, v2
	v_mov_b32_e32 v42, v2
	v_mov_b32_e32 v43, v2
	v_mov_b32_e32 v44, v2
	v_mov_b32_e32 v45, v2
	v_mov_b32_e32 v46, v2
	v_mov_b32_e32 v47, v2
	v_mov_b32_e32 v48, v2
	v_mov_b32_e32 v49, v2
	v_mov_b32_e32 v58, v2
	v_mov_b32_e32 v59, v2
	v_mov_b32_e32 v60, v2
	v_mov_b32_e32 v61, v2
	v_mov_b32_e32 v62, v2
	v_mov_b32_e32 v63, v2
	v_mov_b32_e32 v64, v2
	v_mov_b32_e32 v65, v2
	v_mov_b32_e32 v66, v2
	v_mov_b32_e32 v67, v2
	v_mov_b32_e32 v68, v2
	v_mov_b32_e32 v69, v2
	v_mov_b32_e32 v70, v2
	v_mov_b32_e32 v71, v2
	v_mov_b32_e32 v72, v2
	v_mov_b32_e32 v73, v2
	v_mov_b32_e32 v82, v2
	v_mov_b32_e32 v83, v2
	v_mov_b32_e32 v84, v2
	v_mov_b32_e32 v85, v2
	v_mov_b32_e32 v86, v2
	v_mov_b32_e32 v87, v2
	v_mov_b32_e32 v88, v2
	v_mov_b32_e32 v89, v2
	s_waitcnt vmcnt(0)
	v_mov_b32_e32 v114, v2
	v_mov_b32_e32 v115, v2
	v_mov_b32_e32 v116, v2
	v_mov_b32_e32 v117, v2
	v_mov_b32_e32 v118, v2
	v_mov_b32_e32 v119, v2
	v_mov_b32_e32 v120, v2
	v_mov_b32_e32 v121, v2
	v_mov_b32_e32 v130, v2
	v_mov_b32_e32 v131, v2
	v_mov_b32_e32 v132, v2
	v_mov_b32_e32 v133, v2
	v_mov_b32_e32 v134, v2
	v_mov_b32_e32 v135, v2
	v_mov_b32_e32 v136, v2
	v_mov_b32_e32 v137, v2
	v_mov_b32_e32 v74, v2
	v_mov_b32_e32 v75, v2
	v_mov_b32_e32 v76, v2
	v_mov_b32_e32 v77, v2
	v_mov_b32_e32 v78, v2
	v_mov_b32_e32 v79, v2
	v_mov_b32_e32 v80, v2
	v_mov_b32_e32 v81, v2
	v_mov_b32_e32 v98, v2
	v_mov_b32_e32 v99, v2
	v_mov_b32_e32 v100, v2
	v_mov_b32_e32 v101, v2
	v_mov_b32_e32 v106, v2
	v_mov_b32_e32 v107, v2
	v_mov_b32_e32 v108, v2
	v_mov_b32_e32 v109, v2
	v_mov_b32_e32 v122, v2
	v_mov_b32_e32 v123, v2
	v_mov_b32_e32 v124, v2
	v_mov_b32_e32 v125, v2
	v_mov_b32_e32 v126, v2
	v_mov_b32_e32 v127, v2
	v_mov_b32_e32 v128, v2
	v_mov_b32_e32 v129, v2
	v_mov_b32_e32 v138, v2
	v_mov_b32_e32 v139, v2
	v_mov_b32_e32 v140, v2
	v_mov_b32_e32 v141, v2
	v_mov_b32_e32 v142, v2
	v_mov_b32_e32 v143, v2
	v_mov_b32_e32 v144, v2
	v_mov_b32_e32 v145, v2
	v_add_u32_e32 v246, 0x18000, v186
	v_add_u32_e32 v247, 0x1c000, v186
.LBB0_941:
	ds_read_b128 v[90:93], v188
	ds_read_b128 v[94:97], v188 offset:1024
	ds_read_b128 v[102:105], v188 offset:2048
	ds_read_b128 v[110:113], v188 offset:3072
	ds_read_b128 v[146:149], v189
	ds_read_b128 v[150:153], v189 offset:1024
	ds_read_b128 v[154:157], v189 offset:2048
	ds_read_b128 v[158:161], v189 offset:3072
	s_add_u32 s30, s28, 0xfff00080
	s_addc_u32 s31, s29, -1
	s_cmp_eq_u32 s51, 60
	s_cselect_b32 s35, s21, s31
	s_cselect_b32 s34, s27, s30
	s_cselect_b32 s31, s19, s50
	s_cselect_b32 s30, s48, s49
	s_add_i32 m0, s36, 0xc000
	ds_read_b128 v[178:181], v190
	ds_read_b128 v[182:185], v190 offset:1024
	ds_read_b128 v[192:195], v190 offset:2048
	ds_read_b128 v[196:199], v190 offset:3072
	ds_read_b128 v[200:203], v190 offset:4096
	ds_read_b128 v[204:207], v190 offset:5120
	ds_read_b128 v[208:211], v190 offset:6144
	ds_read_b128 v[212:215], v190 offset:7168
	global_load_lds_dwordx4 v170, s[28:29]
	s_add_i32 m0, s36, 0xe000
	s_nop 0
	global_load_lds_dwordx4 v172, s[28:29]
	s_waitcnt vmcnt(8)
	s_waitcnt lgkmcnt(0)
	s_barrier
	v_mfma_f32_16x16x32_bf16 v[142:145], v[90:93], v[178:181], v[142:145]
	v_mfma_f32_16x16x32_bf16 v[142:145], v[94:97], v[182:185], v[142:145]
	v_mfma_f32_16x16x32_bf16 v[138:141], v[102:105], v[178:181], v[138:141]
	v_mfma_f32_16x16x32_bf16 v[138:141], v[110:113], v[182:185], v[138:141]
	v_mfma_f32_16x16x32_bf16 v[126:129], v[90:93], v[192:195], v[126:129]
	v_mfma_f32_16x16x32_bf16 v[126:129], v[94:97], v[196:199], v[126:129]
	v_mfma_f32_16x16x32_bf16 v[122:125], v[102:105], v[192:195], v[122:125]
	v_mfma_f32_16x16x32_bf16 v[122:125], v[110:113], v[196:199], v[122:125]
	v_mfma_f32_16x16x32_bf16 v[106:109], v[90:93], v[200:203], v[106:109]
	v_mfma_f32_16x16x32_bf16 v[106:109], v[94:97], v[204:207], v[106:109]
	v_mfma_f32_16x16x32_bf16 v[98:101], v[102:105], v[200:203], v[98:101]
	v_mfma_f32_16x16x32_bf16 v[98:101], v[110:113], v[204:207], v[98:101]
	v_mfma_f32_16x16x32_bf16 v[78:81], v[90:93], v[208:211], v[78:81]
	v_mfma_f32_16x16x32_bf16 v[78:81], v[94:97], v[212:215], v[78:81]
	v_mfma_f32_16x16x32_bf16 v[74:77], v[102:105], v[208:211], v[74:77]
	v_mfma_f32_16x16x32_bf16 v[74:77], v[110:113], v[212:215], v[74:77]
	v_mfma_f32_16x16x32_bf16 v[134:137], v[146:149], v[178:181], v[134:137]
	v_mfma_f32_16x16x32_bf16 v[134:137], v[150:153], v[182:185], v[134:137]
	v_mfma_f32_16x16x32_bf16 v[130:133], v[154:157], v[178:181], v[130:133]
	v_mfma_f32_16x16x32_bf16 v[130:133], v[158:161], v[182:185], v[130:133]
	v_mfma_f32_16x16x32_bf16 v[118:121], v[146:149], v[192:195], v[118:121]
	v_mfma_f32_16x16x32_bf16 v[118:121], v[150:153], v[196:199], v[118:121]
	v_mfma_f32_16x16x32_bf16 v[114:117], v[154:157], v[192:195], v[114:117]
	v_mfma_f32_16x16x32_bf16 v[114:117], v[158:161], v[196:199], v[114:117]
	v_mfma_f32_16x16x32_bf16 v[86:89], v[146:149], v[200:203], v[86:89]
	v_mfma_f32_16x16x32_bf16 v[86:89], v[150:153], v[204:207], v[86:89]
	v_mfma_f32_16x16x32_bf16 v[82:85], v[154:157], v[200:203], v[82:85]
	v_mfma_f32_16x16x32_bf16 v[82:85], v[158:161], v[204:207], v[82:85]
	v_mfma_f32_16x16x32_bf16 v[70:73], v[146:149], v[208:211], v[70:73]
	v_mfma_f32_16x16x32_bf16 v[70:73], v[150:153], v[212:215], v[70:73]
	v_mfma_f32_16x16x32_bf16 v[66:69], v[154:157], v[208:211], v[66:69]
	v_mfma_f32_16x16x32_bf16 v[66:69], v[158:161], v[212:215], v[66:69]
	s_barrier
	s_add_i32 s52, s45, s33
	s_mov_b32 m0, s52
	ds_read_b128 v[178:181], v190 offset:16384
	ds_read_b128 v[182:185], v190 offset:17408
	ds_read_b128 v[192:195], v190 offset:18432
	ds_read_b128 v[196:199], v190 offset:19456
	ds_read_b128 v[200:203], v190 offset:20480
	ds_read_b128 v[204:207], v190 offset:21504
	ds_read_b128 v[208:211], v190 offset:22528
	ds_read_b128 v[212:215], v190 offset:23552
	global_load_lds_dwordx4 v164, s[30:31]
	s_add_i32 m0, s52, 0x2000
	s_add_u32 s52, s30, 0x100000
	s_addc_u32 s53, s31, 0
	s_add_i32 s54, s46, s33
	global_load_lds_dwordx4 v168, s[30:31]
	s_mov_b32 m0, s54
	global_load_lds_dwordx4 v164, s[52:53]
	s_add_i32 m0, s54, 0x2000
	s_nop 0
	global_load_lds_dwordx4 v168, s[52:53]
	s_mov_b32 m0, s36
	s_nop 0
	global_load_lds_dwordx4 v162, s[34:35]
	s_mov_b32 m0, s37
	s_nop 0
	global_load_lds_dwordx4 v166, s[34:35]
	s_waitcnt vmcnt(8)
	s_waitcnt lgkmcnt(0)
	s_barrier
	v_mfma_f32_16x16x32_bf16 v[62:65], v[90:93], v[178:181], v[62:65]
	v_mfma_f32_16x16x32_bf16 v[62:65], v[94:97], v[182:185], v[62:65]
	v_mfma_f32_16x16x32_bf16 v[58:61], v[102:105], v[178:181], v[58:61]
	v_mfma_f32_16x16x32_bf16 v[58:61], v[110:113], v[182:185], v[58:61]
	v_mfma_f32_16x16x32_bf16 v[46:49], v[90:93], v[192:195], v[46:49]
	v_mfma_f32_16x16x32_bf16 v[46:49], v[94:97], v[196:199], v[46:49]
	v_mfma_f32_16x16x32_bf16 v[42:45], v[102:105], v[192:195], v[42:45]
	v_mfma_f32_16x16x32_bf16 v[42:45], v[110:113], v[196:199], v[42:45]
	v_mfma_f32_16x16x32_bf16 v[30:33], v[90:93], v[200:203], v[30:33]
	v_mfma_f32_16x16x32_bf16 v[30:33], v[94:97], v[204:207], v[30:33]
	v_mfma_f32_16x16x32_bf16 v[26:29], v[102:105], v[200:203], v[26:29]
	v_mfma_f32_16x16x32_bf16 v[26:29], v[110:113], v[204:207], v[26:29]
	v_mfma_f32_16x16x32_bf16 v[14:17], v[90:93], v[208:211], v[14:17]
	v_mfma_f32_16x16x32_bf16 v[14:17], v[94:97], v[212:215], v[14:17]
	v_mfma_f32_16x16x32_bf16 v[10:13], v[102:105], v[208:211], v[10:13]
	v_mfma_f32_16x16x32_bf16 v[10:13], v[110:113], v[212:215], v[10:13]
	v_mfma_f32_16x16x32_bf16 v[54:57], v[146:149], v[178:181], v[54:57]
	v_mfma_f32_16x16x32_bf16 v[54:57], v[150:153], v[182:185], v[54:57]
	v_mfma_f32_16x16x32_bf16 v[50:53], v[154:157], v[178:181], v[50:53]
	v_mfma_f32_16x16x32_bf16 v[50:53], v[158:161], v[182:185], v[50:53]
	v_mfma_f32_16x16x32_bf16 v[38:41], v[146:149], v[192:195], v[38:41]
	v_mfma_f32_16x16x32_bf16 v[38:41], v[150:153], v[196:199], v[38:41]
	v_mfma_f32_16x16x32_bf16 v[34:37], v[154:157], v[192:195], v[34:37]
	v_mfma_f32_16x16x32_bf16 v[34:37], v[158:161], v[196:199], v[34:37]
	v_mfma_f32_16x16x32_bf16 v[22:25], v[146:149], v[200:203], v[22:25]
	v_mfma_f32_16x16x32_bf16 v[22:25], v[150:153], v[204:207], v[22:25]
	v_mfma_f32_16x16x32_bf16 v[18:21], v[154:157], v[200:203], v[18:21]
	v_mfma_f32_16x16x32_bf16 v[18:21], v[158:161], v[204:207], v[18:21]
	v_mfma_f32_16x16x32_bf16 v[6:9], v[146:149], v[208:211], v[6:9]
	v_mfma_f32_16x16x32_bf16 v[6:9], v[150:153], v[212:215], v[6:9]
	v_mfma_f32_16x16x32_bf16 v[2:5], v[154:157], v[208:211], v[2:5]
	v_mfma_f32_16x16x32_bf16 v[2:5], v[158:161], v[212:215], v[2:5]
	s_barrier
	s_add_i32 s52, 0, 0x18000
	s_add_i32 s53, 0, 0x1c000
	ds_read_b128 v[90:93], v246
	ds_read_b128 v[94:97], v246 offset:1024
	ds_read_b128 v[102:105], v246 offset:2048
	ds_read_b128 v[110:113], v246 offset:3072
	ds_read_b128 v[146:149], v247
	ds_read_b128 v[150:153], v247 offset:1024
	ds_read_b128 v[154:157], v247 offset:2048
	ds_read_b128 v[158:161], v247 offset:3072
	s_add_u32 s98, s34, 0x80
	s_addc_u32 s99, s35, 0
	s_add_u32 s34, s34, 0x100000
	s_addc_u32 s35, s35, 0
	s_mov_b32 m0, s38
	ds_read_b128 v[178:181], v190 offset:32768
	ds_read_b128 v[182:185], v190 offset:33792
	ds_read_b128 v[192:195], v190 offset:34816
	ds_read_b128 v[196:199], v190 offset:35840
	ds_read_b128 v[200:203], v190 offset:36864
	ds_read_b128 v[204:207], v190 offset:37888
	ds_read_b128 v[208:211], v190 offset:38912
	ds_read_b128 v[212:215], v190 offset:39936
	global_load_lds_dwordx4 v162, s[34:35]
	s_mov_b32 m0, s39
	s_nop 0
	global_load_lds_dwordx4 v166, s[34:35]
	s_waitcnt vmcnt(8)
	s_waitcnt lgkmcnt(0)
	s_barrier
	v_mfma_f32_16x16x32_bf16 v[142:145], v[90:93], v[178:181], v[142:145]
	v_mfma_f32_16x16x32_bf16 v[142:145], v[94:97], v[182:185], v[142:145]
	v_mfma_f32_16x16x32_bf16 v[138:141], v[102:105], v[178:181], v[138:141]
	v_mfma_f32_16x16x32_bf16 v[138:141], v[110:113], v[182:185], v[138:141]
	v_mfma_f32_16x16x32_bf16 v[126:129], v[90:93], v[192:195], v[126:129]
	v_mfma_f32_16x16x32_bf16 v[126:129], v[94:97], v[196:199], v[126:129]
	v_mfma_f32_16x16x32_bf16 v[122:125], v[102:105], v[192:195], v[122:125]
	v_mfma_f32_16x16x32_bf16 v[122:125], v[110:113], v[196:199], v[122:125]
	v_mfma_f32_16x16x32_bf16 v[106:109], v[90:93], v[200:203], v[106:109]
	v_mfma_f32_16x16x32_bf16 v[106:109], v[94:97], v[204:207], v[106:109]
	v_mfma_f32_16x16x32_bf16 v[98:101], v[102:105], v[200:203], v[98:101]
	v_mfma_f32_16x16x32_bf16 v[98:101], v[110:113], v[204:207], v[98:101]
	v_mfma_f32_16x16x32_bf16 v[78:81], v[90:93], v[208:211], v[78:81]
	v_mfma_f32_16x16x32_bf16 v[78:81], v[94:97], v[212:215], v[78:81]
	v_mfma_f32_16x16x32_bf16 v[74:77], v[102:105], v[208:211], v[74:77]
	v_mfma_f32_16x16x32_bf16 v[74:77], v[110:113], v[212:215], v[74:77]
	v_mfma_f32_16x16x32_bf16 v[134:137], v[146:149], v[178:181], v[134:137]
	v_mfma_f32_16x16x32_bf16 v[134:137], v[150:153], v[182:185], v[134:137]
	v_mfma_f32_16x16x32_bf16 v[130:133], v[154:157], v[178:181], v[130:133]
	v_mfma_f32_16x16x32_bf16 v[130:133], v[158:161], v[182:185], v[130:133]
	v_mfma_f32_16x16x32_bf16 v[118:121], v[146:149], v[192:195], v[118:121]
	v_mfma_f32_16x16x32_bf16 v[118:121], v[150:153], v[196:199], v[118:121]
	v_mfma_f32_16x16x32_bf16 v[114:117], v[154:157], v[192:195], v[114:117]
	v_mfma_f32_16x16x32_bf16 v[114:117], v[158:161], v[196:199], v[114:117]
	v_mfma_f32_16x16x32_bf16 v[86:89], v[146:149], v[200:203], v[86:89]
	v_mfma_f32_16x16x32_bf16 v[86:89], v[150:153], v[204:207], v[86:89]
	v_mfma_f32_16x16x32_bf16 v[82:85], v[154:157], v[200:203], v[82:85]
	v_mfma_f32_16x16x32_bf16 v[82:85], v[158:161], v[204:207], v[82:85]
	v_mfma_f32_16x16x32_bf16 v[70:73], v[146:149], v[208:211], v[70:73]
	v_mfma_f32_16x16x32_bf16 v[70:73], v[150:153], v[212:215], v[70:73]
	v_mfma_f32_16x16x32_bf16 v[66:69], v[154:157], v[208:211], v[66:69]
	v_mfma_f32_16x16x32_bf16 v[66:69], v[158:161], v[212:215], v[66:69]
	s_barrier
	s_add_i32 s34, s52, s33
	s_mov_b32 m0, s34
	ds_read_b128 v[178:181], v190 offset:49152
	ds_read_b128 v[182:185], v190 offset:50176
	ds_read_b128 v[192:195], v190 offset:51200
	ds_read_b128 v[196:199], v190 offset:52224
	ds_read_b128 v[200:203], v190 offset:53248
	ds_read_b128 v[204:207], v190 offset:54272
	ds_read_b128 v[208:211], v190 offset:55296
	ds_read_b128 v[212:215], v190 offset:56320
	s_add_u32 s30, s30, 0x80
	s_addc_u32 s31, s31, 0
	global_load_lds_dwordx4 v164, s[30:31]
	s_add_i32 m0, s34, 0x2000
	s_add_i32 s34, s53, s33
	global_load_lds_dwordx4 v168, s[30:31]
	s_add_u32 s30, s30, 0x100000
	s_addc_u32 s31, s31, 0
	s_mov_b32 m0, s34
	s_nop 0
	global_load_lds_dwordx4 v164, s[30:31]
	s_add_i32 m0, s34, 0x2000
	s_nop 0
	global_load_lds_dwordx4 v168, s[30:31]
	s_mov_b32 m0, s43
	s_nop 0
	global_load_lds_dwordx4 v162, s[98:99]
	s_mov_b32 m0, s44
	s_nop 0
	global_load_lds_dwordx4 v166, s[98:99]
	s_waitcnt vmcnt(8)
	s_waitcnt lgkmcnt(0)
	s_barrier
	v_mfma_f32_16x16x32_bf16 v[62:65], v[90:93], v[178:181], v[62:65]
	v_mfma_f32_16x16x32_bf16 v[62:65], v[94:97], v[182:185], v[62:65]
	v_mfma_f32_16x16x32_bf16 v[58:61], v[102:105], v[178:181], v[58:61]
	v_mfma_f32_16x16x32_bf16 v[58:61], v[110:113], v[182:185], v[58:61]
	v_mfma_f32_16x16x32_bf16 v[46:49], v[90:93], v[192:195], v[46:49]
	v_mfma_f32_16x16x32_bf16 v[46:49], v[94:97], v[196:199], v[46:49]
	v_mfma_f32_16x16x32_bf16 v[42:45], v[102:105], v[192:195], v[42:45]
	v_mfma_f32_16x16x32_bf16 v[42:45], v[110:113], v[196:199], v[42:45]
	v_mfma_f32_16x16x32_bf16 v[30:33], v[90:93], v[200:203], v[30:33]
	v_mfma_f32_16x16x32_bf16 v[30:33], v[94:97], v[204:207], v[30:33]
	v_mfma_f32_16x16x32_bf16 v[26:29], v[102:105], v[200:203], v[26:29]
	v_mfma_f32_16x16x32_bf16 v[26:29], v[110:113], v[204:207], v[26:29]
	v_mfma_f32_16x16x32_bf16 v[14:17], v[90:93], v[208:211], v[14:17]
	v_mfma_f32_16x16x32_bf16 v[14:17], v[94:97], v[212:215], v[14:17]
	v_mfma_f32_16x16x32_bf16 v[10:13], v[102:105], v[208:211], v[10:13]
	v_mfma_f32_16x16x32_bf16 v[10:13], v[110:113], v[212:215], v[10:13]
	v_mfma_f32_16x16x32_bf16 v[54:57], v[146:149], v[178:181], v[54:57]
	v_mfma_f32_16x16x32_bf16 v[54:57], v[150:153], v[182:185], v[54:57]
	v_mfma_f32_16x16x32_bf16 v[50:53], v[154:157], v[178:181], v[50:53]
	v_mfma_f32_16x16x32_bf16 v[50:53], v[158:161], v[182:185], v[50:53]
	v_mfma_f32_16x16x32_bf16 v[38:41], v[146:149], v[192:195], v[38:41]
	v_mfma_f32_16x16x32_bf16 v[38:41], v[150:153], v[196:199], v[38:41]
	v_mfma_f32_16x16x32_bf16 v[34:37], v[154:157], v[192:195], v[34:37]
	v_mfma_f32_16x16x32_bf16 v[34:37], v[158:161], v[196:199], v[34:37]
	v_mfma_f32_16x16x32_bf16 v[22:25], v[146:149], v[200:203], v[22:25]
	v_mfma_f32_16x16x32_bf16 v[22:25], v[150:153], v[204:207], v[22:25]
	v_mfma_f32_16x16x32_bf16 v[18:21], v[154:157], v[200:203], v[18:21]
	v_mfma_f32_16x16x32_bf16 v[18:21], v[158:161], v[204:207], v[18:21]
	v_mfma_f32_16x16x32_bf16 v[6:9], v[146:149], v[208:211], v[6:9]
	v_mfma_f32_16x16x32_bf16 v[6:9], v[150:153], v[212:215], v[6:9]
	v_mfma_f32_16x16x32_bf16 v[2:5], v[154:157], v[208:211], v[2:5]
	v_mfma_f32_16x16x32_bf16 v[2:5], v[158:161], v[212:215], v[2:5]
	s_barrier
	s_add_i32 s51, s51, 2
	s_add_u32 s28, s28, 0x100
	s_addc_u32 s29, s29, 0
	s_add_u32 s49, s49, 0x100
	s_addc_u32 s50, s50, 0
	s_cmp_gt_u32 s51, 61
	s_cbranch_scc0 .LBB0_941
	s_and_b64 vcc, exec, s[16:17]
	s_cbranch_vccz .LBB0_944
	s_barrier

.LBB0_1152:
	s_xor_b64 s[48:49], s[54:55], -1
	s_add_u32 s33, s56, 0x100
	s_addc_u32 s72, s57, 0
	s_ashr_i32 s45, s44, 31
	s_lshl_b64 s[50:51], s[44:45], 21
	s_add_u32 s50, s70, s50
	s_addc_u32 s51, s71, s51
	s_and_b64 s[52:53], s[54:55], exec
	s_cselect_b32 s29, s51, s47
	s_cselect_b32 s45, s50, s46
	s_ashr_i32 s43, s42, 31
	s_lshl_b64 s[52:53], s[42:43], 21
	v_readlane_b32 s20, v244, 4
	v_readlane_b32 s21, v244, 5
	s_add_u32 s52, s20, s52
	s_addc_u32 s53, s21, s53
	s_and_b64 s[58:59], s[54:55], exec
	s_cselect_b32 s43, s53, s57
	s_cselect_b32 s73, s52, s56
	v_lshl_add_u64 v[130:131], s[46:47], 0, v[196:197]
	v_lshl_add_u64 v[132:133], s[46:47], 0, v[198:199]
	s_mov_b32 s83, -2
	v_add_u32_e32 v246, 0x18000, v187
	v_add_u32_e32 v247, 0x1c000, v187
.LBB0_1153:
	v_add_u32_e32 v146, s78, v187
	v_add_u32_e32 v162, s79, v187
	s_add_u32 s98, s46, s10
	s_addc_u32 s99, s47, s11
	s_add_u32 s98, s98, 0x100080
	s_addc_u32 s99, s99, 0
	s_add_u32 s56, s46, s10
	ds_read_b128 v[134:137], v146
	ds_read_b128 v[138:141], v146 offset:1024
	ds_read_b128 v[142:145], v146 offset:2048
	ds_read_b128 v[146:149], v146 offset:3072
	ds_read_b128 v[150:153], v162
	ds_read_b128 v[154:157], v162 offset:1024
	ds_read_b128 v[158:161], v162 offset:2048
	ds_read_b128 v[162:165], v162 offset:3072
	s_addc_u32 s57, s47, s11
	s_add_u32 s56, s56, 0x100
	s_addc_u32 s57, s57, 0
	s_add_u32 s84, s33, s10
	s_addc_u32 s85, s72, s11
	s_cmpk_eq_i32 s10, 0x1f00
	s_cselect_b32 s59, s29, s57
	s_cselect_b32 s58, s45, s56
	s_cselect_b32 s57, s43, s85
	s_cselect_b32 s56, s73, s84
	s_add_i32 m0, s64, 0xc000
	ds_read_b128 v[166:169], v230
	ds_read_b128 v[170:173], v230 offset:1024
	ds_read_b128 v[174:177], v230 offset:2048
	ds_read_b128 v[202:205], v230 offset:3072
	ds_read_b128 v[206:209], v230 offset:4096
	ds_read_b128 v[210:213], v230 offset:5120
	ds_read_b128 v[214:217], v230 offset:6144
	ds_read_b128 v[218:221], v230 offset:7168
	global_load_lds_dwordx4 v178, s[98:99]
	s_add_i32 m0, s64, 0xe000
	s_nop 0
	global_load_lds_dwordx4 v182, s[98:99]
	s_waitcnt vmcnt(8)
	s_waitcnt lgkmcnt(0)
	s_barrier
	v_mfma_f32_16x16x32_bf16 v[2:5], v[134:137], v[166:169], v[2:5]
	v_mfma_f32_16x16x32_bf16 v[2:5], v[138:141], v[170:173], v[2:5]
	v_mfma_f32_16x16x32_bf16 v[126:129], v[142:145], v[166:169], v[126:129]
	v_mfma_f32_16x16x32_bf16 v[126:129], v[146:149], v[170:173], v[126:129]
	v_mfma_f32_16x16x32_bf16 v[122:125], v[134:137], v[174:177], v[122:125]
	v_mfma_f32_16x16x32_bf16 v[122:125], v[138:141], v[202:205], v[122:125]
	v_mfma_f32_16x16x32_bf16 v[118:121], v[142:145], v[174:177], v[118:121]
	v_mfma_f32_16x16x32_bf16 v[118:121], v[146:149], v[202:205], v[118:121]
	v_mfma_f32_16x16x32_bf16 v[114:117], v[134:137], v[206:209], v[114:117]
	v_mfma_f32_16x16x32_bf16 v[114:117], v[138:141], v[210:213], v[114:117]
	v_mfma_f32_16x16x32_bf16 v[110:113], v[142:145], v[206:209], v[110:113]
	v_mfma_f32_16x16x32_bf16 v[110:113], v[146:149], v[210:213], v[110:113]
	v_mfma_f32_16x16x32_bf16 v[106:109], v[134:137], v[214:217], v[106:109]
	v_mfma_f32_16x16x32_bf16 v[106:109], v[138:141], v[218:221], v[106:109]
	v_mfma_f32_16x16x32_bf16 v[102:105], v[142:145], v[214:217], v[102:105]
	v_mfma_f32_16x16x32_bf16 v[102:105], v[146:149], v[218:221], v[102:105]
	v_mfma_f32_16x16x32_bf16 v[98:101], v[150:153], v[166:169], v[98:101]
	v_mfma_f32_16x16x32_bf16 v[98:101], v[154:157], v[170:173], v[98:101]
	v_mfma_f32_16x16x32_bf16 v[94:97], v[158:161], v[166:169], v[94:97]
	v_mfma_f32_16x16x32_bf16 v[94:97], v[162:165], v[170:173], v[94:97]
	v_mfma_f32_16x16x32_bf16 v[90:93], v[150:153], v[174:177], v[90:93]
	v_mfma_f32_16x16x32_bf16 v[90:93], v[154:157], v[202:205], v[90:93]
	v_mfma_f32_16x16x32_bf16 v[86:89], v[158:161], v[174:177], v[86:89]
	v_mfma_f32_16x16x32_bf16 v[86:89], v[162:165], v[202:205], v[86:89]
	v_mfma_f32_16x16x32_bf16 v[82:85], v[150:153], v[206:209], v[82:85]
	v_mfma_f32_16x16x32_bf16 v[82:85], v[154:157], v[210:213], v[82:85]
	v_mfma_f32_16x16x32_bf16 v[78:81], v[158:161], v[206:209], v[78:81]
	v_mfma_f32_16x16x32_bf16 v[78:81], v[162:165], v[210:213], v[78:81]
	v_mfma_f32_16x16x32_bf16 v[74:77], v[150:153], v[214:217], v[74:77]
	v_mfma_f32_16x16x32_bf16 v[74:77], v[154:157], v[218:221], v[74:77]
	v_mfma_f32_16x16x32_bf16 v[70:73], v[158:161], v[214:217], v[70:73]
	v_mfma_f32_16x16x32_bf16 v[70:73], v[162:165], v[218:221], v[70:73]
	s_barrier
	s_add_i32 s84, s78, s63
	s_mov_b32 m0, s84
	ds_read_b128 v[166:169], v230 offset:16384
	ds_read_b128 v[170:173], v230 offset:17408
	ds_read_b128 v[174:177], v230 offset:18432
	ds_read_b128 v[202:205], v230 offset:19456
	ds_read_b128 v[206:209], v230 offset:20480
	ds_read_b128 v[210:213], v230 offset:21504
	ds_read_b128 v[214:217], v230 offset:22528
	ds_read_b128 v[218:221], v230 offset:23552
	global_load_lds_dwordx4 v180, s[56:57]
	s_add_i32 m0, s84, 0x2000
	s_add_u32 s84, s56, 0x100000
	s_addc_u32 s85, s57, 0
	s_add_i32 s86, s79, s63
	global_load_lds_dwordx4 v184, s[56:57]
	s_mov_b32 m0, s86
	s_nop 0
	global_load_lds_dwordx4 v180, s[84:85]
	s_add_i32 m0, s86, 0x2000
	s_nop 0
	global_load_lds_dwordx4 v184, s[84:85]
	s_mov_b32 m0, s64
	s_nop 0
	global_load_lds_dwordx4 v178, s[58:59]
	s_mov_b32 m0, s65
	s_nop 0
	global_load_lds_dwordx4 v182, s[58:59]
	s_waitcnt vmcnt(8)
	s_waitcnt lgkmcnt(0)
	s_barrier
	v_mfma_f32_16x16x32_bf16 v[66:69], v[134:137], v[166:169], v[66:69]
	v_mfma_f32_16x16x32_bf16 v[66:69], v[138:141], v[170:173], v[66:69]
	v_mfma_f32_16x16x32_bf16 v[62:65], v[142:145], v[166:169], v[62:65]
	v_mfma_f32_16x16x32_bf16 v[62:65], v[146:149], v[170:173], v[62:65]
	v_mfma_f32_16x16x32_bf16 v[58:61], v[134:137], v[174:177], v[58:61]
	v_mfma_f32_16x16x32_bf16 v[58:61], v[138:141], v[202:205], v[58:61]
	v_mfma_f32_16x16x32_bf16 v[54:57], v[142:145], v[174:177], v[54:57]
	v_mfma_f32_16x16x32_bf16 v[54:57], v[146:149], v[202:205], v[54:57]
	v_mfma_f32_16x16x32_bf16 v[50:53], v[134:137], v[206:209], v[50:53]
	v_mfma_f32_16x16x32_bf16 v[50:53], v[138:141], v[210:213], v[50:53]
	v_mfma_f32_16x16x32_bf16 v[46:49], v[142:145], v[206:209], v[46:49]
	v_mfma_f32_16x16x32_bf16 v[46:49], v[146:149], v[210:213], v[46:49]
	v_mfma_f32_16x16x32_bf16 v[42:45], v[134:137], v[214:217], v[42:45]
	v_mfma_f32_16x16x32_bf16 v[42:45], v[138:141], v[218:221], v[42:45]
	v_mfma_f32_16x16x32_bf16 v[38:41], v[142:145], v[214:217], v[38:41]
	v_mfma_f32_16x16x32_bf16 v[38:41], v[146:149], v[218:221], v[38:41]
	v_mfma_f32_16x16x32_bf16 v[34:37], v[150:153], v[166:169], v[34:37]
	v_mfma_f32_16x16x32_bf16 v[34:37], v[154:157], v[170:173], v[34:37]
	v_mfma_f32_16x16x32_bf16 v[30:33], v[158:161], v[166:169], v[30:33]
	v_mfma_f32_16x16x32_bf16 v[30:33], v[162:165], v[170:173], v[30:33]
	v_mfma_f32_16x16x32_bf16 v[26:29], v[150:153], v[174:177], v[26:29]
	v_mfma_f32_16x16x32_bf16 v[26:29], v[154:157], v[202:205], v[26:29]
	v_mfma_f32_16x16x32_bf16 v[22:25], v[158:161], v[174:177], v[22:25]
	v_mfma_f32_16x16x32_bf16 v[22:25], v[162:165], v[202:205], v[22:25]
	v_mfma_f32_16x16x32_bf16 v[18:21], v[150:153], v[206:209], v[18:21]
	v_mfma_f32_16x16x32_bf16 v[18:21], v[154:157], v[210:213], v[18:21]
	v_mfma_f32_16x16x32_bf16 v[14:17], v[158:161], v[206:209], v[14:17]
	v_mfma_f32_16x16x32_bf16 v[14:17], v[162:165], v[210:213], v[14:17]
	v_mfma_f32_16x16x32_bf16 v[10:13], v[150:153], v[214:217], v[10:13]
	v_mfma_f32_16x16x32_bf16 v[10:13], v[154:157], v[218:221], v[10:13]
	v_mfma_f32_16x16x32_bf16 v[6:9], v[158:161], v[214:217], v[6:9]
	v_mfma_f32_16x16x32_bf16 v[6:9], v[162:165], v[218:221], v[6:9]
	s_barrier
	s_add_i32 s84, 0, 0x18000
	s_add_i32 s85, 0, 0x1c000
	ds_read_b128 v[134:137], v246
	ds_read_b128 v[138:141], v246 offset:1024
	ds_read_b128 v[142:145], v246 offset:2048
	ds_read_b128 v[146:149], v246 offset:3072
	ds_read_b128 v[150:153], v247
	ds_read_b128 v[154:157], v247 offset:1024
	ds_read_b128 v[158:161], v247 offset:2048
	ds_read_b128 v[162:165], v247 offset:3072
	s_add_u32 s100, s58, 0x80
	s_addc_u32 s101, s59, 0
	s_add_u32 s58, s58, 0x100000
	s_addc_u32 s59, s59, 0
	s_mov_b32 m0, s67
	ds_read_b128 v[166:169], v230 offset:32768
	ds_read_b128 v[170:173], v230 offset:33792
	ds_read_b128 v[174:177], v230 offset:34816
	ds_read_b128 v[202:205], v230 offset:35840
	ds_read_b128 v[206:209], v230 offset:36864
	ds_read_b128 v[210:213], v230 offset:37888
	ds_read_b128 v[214:217], v230 offset:38912
	ds_read_b128 v[218:221], v230 offset:39936
	global_load_lds_dwordx4 v178, s[58:59]
	s_mov_b32 m0, s68
	s_nop 0
	global_load_lds_dwordx4 v182, s[58:59]
	s_waitcnt vmcnt(8)
	s_waitcnt lgkmcnt(0)
	s_barrier
	v_mfma_f32_16x16x32_bf16 v[2:5], v[134:137], v[166:169], v[2:5]
	v_mfma_f32_16x16x32_bf16 v[2:5], v[138:141], v[170:173], v[2:5]
	v_mfma_f32_16x16x32_bf16 v[126:129], v[142:145], v[166:169], v[126:129]
	v_mfma_f32_16x16x32_bf16 v[126:129], v[146:149], v[170:173], v[126:129]
	v_mfma_f32_16x16x32_bf16 v[122:125], v[134:137], v[174:177], v[122:125]
	v_mfma_f32_16x16x32_bf16 v[122:125], v[138:141], v[202:205], v[122:125]
	v_mfma_f32_16x16x32_bf16 v[118:121], v[142:145], v[174:177], v[118:121]
	v_mfma_f32_16x16x32_bf16 v[118:121], v[146:149], v[202:205], v[118:121]
	v_mfma_f32_16x16x32_bf16 v[114:117], v[134:137], v[206:209], v[114:117]
	v_mfma_f32_16x16x32_bf16 v[114:117], v[138:141], v[210:213], v[114:117]
	v_mfma_f32_16x16x32_bf16 v[110:113], v[142:145], v[206:209], v[110:113]
	v_mfma_f32_16x16x32_bf16 v[110:113], v[146:149], v[210:213], v[110:113]
	v_mfma_f32_16x16x32_bf16 v[106:109], v[134:137], v[214:217], v[106:109]
	v_mfma_f32_16x16x32_bf16 v[106:109], v[138:141], v[218:221], v[106:109]
	v_mfma_f32_16x16x32_bf16 v[102:105], v[142:145], v[214:217], v[102:105]
	v_mfma_f32_16x16x32_bf16 v[102:105], v[146:149], v[218:221], v[102:105]
	v_mfma_f32_16x16x32_bf16 v[98:101], v[150:153], v[166:169], v[98:101]
	v_mfma_f32_16x16x32_bf16 v[98:101], v[154:157], v[170:173], v[98:101]
	v_mfma_f32_16x16x32_bf16 v[94:97], v[158:161], v[166:169], v[94:97]
	v_mfma_f32_16x16x32_bf16 v[94:97], v[162:165], v[170:173], v[94:97]
	v_mfma_f32_16x16x32_bf16 v[90:93], v[150:153], v[174:177], v[90:93]
	v_mfma_f32_16x16x32_bf16 v[90:93], v[154:157], v[202:205], v[90:93]
	v_mfma_f32_16x16x32_bf16 v[86:89], v[158:161], v[174:177], v[86:89]
	v_mfma_f32_16x16x32_bf16 v[86:89], v[162:165], v[202:205], v[86:89]
	v_mfma_f32_16x16x32_bf16 v[82:85], v[150:153], v[206:209], v[82:85]
	v_mfma_f32_16x16x32_bf16 v[82:85], v[154:157], v[210:213], v[82:85]
	v_mfma_f32_16x16x32_bf16 v[78:81], v[158:161], v[206:209], v[78:81]
	v_mfma_f32_16x16x32_bf16 v[78:81], v[162:165], v[210:213], v[78:81]
	v_mfma_f32_16x16x32_bf16 v[74:77], v[150:153], v[214:217], v[74:77]
	v_mfma_f32_16x16x32_bf16 v[74:77], v[154:157], v[218:221], v[74:77]
	v_mfma_f32_16x16x32_bf16 v[70:73], v[158:161], v[214:217], v[70:73]
	v_mfma_f32_16x16x32_bf16 v[70:73], v[162:165], v[218:221], v[70:73]
	s_barrier
	s_add_i32 s58, s84, s63
	s_add_u32 s98, s56, 0x80
	s_addc_u32 s99, s57, 0
	s_mov_b32 m0, s58
	ds_read_b128 v[166:169], v230 offset:49152
	ds_read_b128 v[170:173], v230 offset:50176
	ds_read_b128 v[174:177], v230 offset:51200
	ds_read_b128 v[202:205], v230 offset:52224
	ds_read_b128 v[206:209], v230 offset:53248
	ds_read_b128 v[210:213], v230 offset:54272
	ds_read_b128 v[214:217], v230 offset:55296
	ds_read_b128 v[218:221], v230 offset:56320
	global_load_lds_dwordx4 v180, s[98:99]
	s_add_i32 m0, s58, 0x2000
	s_add_u32 s56, s56, 0x100080
	s_addc_u32 s57, s57, 0
	s_add_i32 s58, s85, s63
	global_load_lds_dwordx4 v184, s[98:99]
	s_mov_b32 m0, s58
	s_nop 0
	global_load_lds_dwordx4 v180, s[56:57]
	s_add_i32 m0, s58, 0x2000
	s_nop 0
	global_load_lds_dwordx4 v184, s[56:57]
	s_mov_b32 m0, s74
	s_nop 0
	global_load_lds_dwordx4 v178, s[100:101]
	s_mov_b32 m0, s75
	s_nop 0
	global_load_lds_dwordx4 v182, s[100:101]
	s_waitcnt vmcnt(8)
	s_waitcnt lgkmcnt(0)
	s_barrier
	v_mfma_f32_16x16x32_bf16 v[66:69], v[134:137], v[166:169], v[66:69]
	v_mfma_f32_16x16x32_bf16 v[66:69], v[138:141], v[170:173], v[66:69]
	v_mfma_f32_16x16x32_bf16 v[62:65], v[142:145], v[166:169], v[62:65]
	v_mfma_f32_16x16x32_bf16 v[62:65], v[146:149], v[170:173], v[62:65]
	v_mfma_f32_16x16x32_bf16 v[58:61], v[134:137], v[174:177], v[58:61]
	v_mfma_f32_16x16x32_bf16 v[58:61], v[138:141], v[202:205], v[58:61]
	v_mfma_f32_16x16x32_bf16 v[54:57], v[142:145], v[174:177], v[54:57]
	v_mfma_f32_16x16x32_bf16 v[54:57], v[146:149], v[202:205], v[54:57]
	v_mfma_f32_16x16x32_bf16 v[50:53], v[134:137], v[206:209], v[50:53]
	v_mfma_f32_16x16x32_bf16 v[50:53], v[138:141], v[210:213], v[50:53]
	v_mfma_f32_16x16x32_bf16 v[46:49], v[142:145], v[206:209], v[46:49]
	v_mfma_f32_16x16x32_bf16 v[46:49], v[146:149], v[210:213], v[46:49]
	v_mfma_f32_16x16x32_bf16 v[42:45], v[134:137], v[214:217], v[42:45]
	v_mfma_f32_16x16x32_bf16 v[42:45], v[138:141], v[218:221], v[42:45]
	v_mfma_f32_16x16x32_bf16 v[38:41], v[142:145], v[214:217], v[38:41]
	v_mfma_f32_16x16x32_bf16 v[38:41], v[146:149], v[218:221], v[38:41]
	v_mfma_f32_16x16x32_bf16 v[34:37], v[150:153], v[166:169], v[34:37]
	v_mfma_f32_16x16x32_bf16 v[34:37], v[154:157], v[170:173], v[34:37]
	v_mfma_f32_16x16x32_bf16 v[30:33], v[158:161], v[166:169], v[30:33]
	v_mfma_f32_16x16x32_bf16 v[30:33], v[162:165], v[170:173], v[30:33]
	v_mfma_f32_16x16x32_bf16 v[26:29], v[150:153], v[174:177], v[26:29]
	v_mfma_f32_16x16x32_bf16 v[26:29], v[154:157], v[202:205], v[26:29]
	v_mfma_f32_16x16x32_bf16 v[22:25], v[158:161], v[174:177], v[22:25]
	v_mfma_f32_16x16x32_bf16 v[22:25], v[162:165], v[202:205], v[22:25]
	v_mfma_f32_16x16x32_bf16 v[18:21], v[150:153], v[206:209], v[18:21]
	v_mfma_f32_16x16x32_bf16 v[18:21], v[154:157], v[210:213], v[18:21]
	v_mfma_f32_16x16x32_bf16 v[14:17], v[158:161], v[206:209], v[14:17]
	v_mfma_f32_16x16x32_bf16 v[14:17], v[162:165], v[210:213], v[14:17]
	v_mfma_f32_16x16x32_bf16 v[10:13], v[150:153], v[214:217], v[10:13]
	v_mfma_f32_16x16x32_bf16 v[10:13], v[154:157], v[218:221], v[10:13]
	v_mfma_f32_16x16x32_bf16 v[6:9], v[158:161], v[214:217], v[6:9]
	v_mfma_f32_16x16x32_bf16 v[6:9], v[162:165], v[218:221], v[6:9]
	s_barrier
	s_add_i32 s83, s83, 2
	s_add_u32 s10, s10, 0x100
	s_addc_u32 s11, s11, 0
	s_cmp_gt_u32 s83, 61
	s_cbranch_scc0 .LBB0_1153
	s_and_b64 vcc, exec, s[36:37]
	s_cbranch_vccz .LBB0_1156
	s_barrier

.LBB0_1324:
	s_add_u32 s24, s24, 0x2b0080
	s_addc_u32 s25, s25, 0
	s_add_u32 s47, s26, 0x100
	v_mov_b32_e32 v2, 0
	s_addc_u32 s48, s27, 0
	s_mov_b32 s49, -2
	v_mov_b32_e32 v3, v2
	v_mov_b32_e32 v4, v2
	v_mov_b32_e32 v5, v2
	v_mov_b32_e32 v6, v2
	v_mov_b32_e32 v7, v2
	v_mov_b32_e32 v8, v2
	v_mov_b32_e32 v9, v2
	v_mov_b32_e32 v18, v2
	v_mov_b32_e32 v19, v2
	v_mov_b32_e32 v20, v2
	v_mov_b32_e32 v21, v2
	v_mov_b32_e32 v22, v2
	v_mov_b32_e32 v23, v2
	v_mov_b32_e32 v24, v2
	v_mov_b32_e32 v25, v2
	v_mov_b32_e32 v34, v2
	v_mov_b32_e32 v35, v2
	v_mov_b32_e32 v36, v2
	v_mov_b32_e32 v37, v2
	v_mov_b32_e32 v38, v2
	v_mov_b32_e32 v39, v2
	v_mov_b32_e32 v40, v2
	v_mov_b32_e32 v41, v2
	v_mov_b32_e32 v50, v2
	v_mov_b32_e32 v51, v2
	v_mov_b32_e32 v52, v2
	v_mov_b32_e32 v53, v2
	v_mov_b32_e32 v54, v2
	v_mov_b32_e32 v55, v2
	v_mov_b32_e32 v56, v2
	v_mov_b32_e32 v57, v2
	v_mov_b32_e32 v10, v2
	v_mov_b32_e32 v11, v2
	v_mov_b32_e32 v12, v2
	v_mov_b32_e32 v13, v2
	v_mov_b32_e32 v14, v2
	v_mov_b32_e32 v15, v2
	v_mov_b32_e32 v16, v2
	v_mov_b32_e32 v17, v2
	v_mov_b32_e32 v26, v2
	v_mov_b32_e32 v27, v2
	v_mov_b32_e32 v28, v2
	v_mov_b32_e32 v29, v2
	v_mov_b32_e32 v30, v2
	v_mov_b32_e32 v31, v2
	v_mov_b32_e32 v32, v2
	v_mov_b32_e32 v33, v2
	v_mov_b32_e32 v42, v2
	v_mov_b32_e32 v43, v2
	v_mov_b32_e32 v44, v2
	v_mov_b32_e32 v45, v2
	v_mov_b32_e32 v46, v2
	v_mov_b32_e32 v47, v2
	v_mov_b32_e32 v48, v2
	v_mov_b32_e32 v49, v2
	v_mov_b32_e32 v58, v2
	v_mov_b32_e32 v59, v2
	v_mov_b32_e32 v60, v2
	v_mov_b32_e32 v61, v2
	v_mov_b32_e32 v62, v2
	v_mov_b32_e32 v63, v2
	v_mov_b32_e32 v64, v2
	v_mov_b32_e32 v65, v2
	v_mov_b32_e32 v66, v2
	v_mov_b32_e32 v67, v2
	v_mov_b32_e32 v68, v2
	v_mov_b32_e32 v69, v2
	v_mov_b32_e32 v70, v2
	v_mov_b32_e32 v71, v2
	v_mov_b32_e32 v72, v2
	v_mov_b32_e32 v73, v2
	v_mov_b32_e32 v82, v2
	v_mov_b32_e32 v83, v2
	v_mov_b32_e32 v84, v2
	v_mov_b32_e32 v85, v2
	v_mov_b32_e32 v86, v2
	v_mov_b32_e32 v87, v2
	v_mov_b32_e32 v88, v2
	v_mov_b32_e32 v89, v2
	s_waitcnt vmcnt(0)
	v_mov_b32_e32 v98, v2
	v_mov_b32_e32 v99, v2
	v_mov_b32_e32 v100, v2
	v_mov_b32_e32 v101, v2
	v_mov_b32_e32 v102, v2
	v_mov_b32_e32 v103, v2
	v_mov_b32_e32 v104, v2
	v_mov_b32_e32 v105, v2
	v_mov_b32_e32 v114, v2
	v_mov_b32_e32 v115, v2
	v_mov_b32_e32 v116, v2
	v_mov_b32_e32 v117, v2
	v_mov_b32_e32 v118, v2
	v_mov_b32_e32 v119, v2
	v_mov_b32_e32 v120, v2
	v_mov_b32_e32 v121, v2
	v_mov_b32_e32 v74, v2
	v_mov_b32_e32 v75, v2
	v_mov_b32_e32 v76, v2
	v_mov_b32_e32 v77, v2
	v_mov_b32_e32 v78, v2
	v_mov_b32_e32 v79, v2
	v_mov_b32_e32 v80, v2
	v_mov_b32_e32 v81, v2
	v_mov_b32_e32 v90, v2
	v_mov_b32_e32 v91, v2
	v_mov_b32_e32 v92, v2
	v_mov_b32_e32 v93, v2
	v_mov_b32_e32 v94, v2
	v_mov_b32_e32 v95, v2
	v_mov_b32_e32 v96, v2
	v_mov_b32_e32 v97, v2
	v_mov_b32_e32 v106, v2
	v_mov_b32_e32 v107, v2
	v_mov_b32_e32 v108, v2
	v_mov_b32_e32 v109, v2
	v_mov_b32_e32 v110, v2
	v_mov_b32_e32 v111, v2
	v_mov_b32_e32 v112, v2
	v_mov_b32_e32 v113, v2
	v_mov_b32_e32 v122, v2
	v_mov_b32_e32 v123, v2
	v_mov_b32_e32 v124, v2
	v_mov_b32_e32 v125, v2
	v_mov_b32_e32 v126, v2
	v_mov_b32_e32 v127, v2
	v_mov_b32_e32 v128, v2
	v_mov_b32_e32 v129, v2
	v_add_u32_e32 v246, 0x18000, v174
	v_add_u32_e32 v247, 0x1c000, v174
.LBB0_1325:
	ds_read_b128 v[130:133], v176
	ds_read_b128 v[134:137], v176 offset:1024
	ds_read_b128 v[138:141], v176 offset:2048
	ds_read_b128 v[142:145], v176 offset:3072
	ds_read_b128 v[146:149], v177
	ds_read_b128 v[166:169], v177 offset:1024
	ds_read_b128 v[170:173], v177 offset:2048
	ds_read_b128 v[180:183], v177 offset:3072
	s_add_u32 s26, s24, 0xffd50080
	s_addc_u32 s27, s25, -1
	s_cmpk_eq_i32 s49, 0xa8
	s_cselect_b32 s29, s5, s27
	s_cselect_b32 s28, s4, s26
	s_cselect_b32 s27, s23, s48
	s_cselect_b32 s26, s22, s47
	s_add_i32 m0, s33, 0xc000
	ds_read_b128 v[184:187], v178
	ds_read_b128 v[188:191], v178 offset:1024
	ds_read_b128 v[192:195], v178 offset:2048
	ds_read_b128 v[196:199], v178 offset:3072
	ds_read_b128 v[200:203], v178 offset:4096
	ds_read_b128 v[204:207], v178 offset:5120
	ds_read_b128 v[208:211], v178 offset:6144
	ds_read_b128 v[212:215], v178 offset:7168
	global_load_lds_dwordx4 v158, s[24:25]
	s_add_i32 m0, s33, 0xe000
	s_nop 0
	global_load_lds_dwordx4 v160, s[24:25]
	s_waitcnt vmcnt(8)
	s_waitcnt lgkmcnt(0)
	s_barrier
	v_mfma_f32_16x16x32_bf16 v[126:129], v[130:133], v[184:187], v[126:129]
	v_mfma_f32_16x16x32_bf16 v[126:129], v[134:137], v[188:191], v[126:129]
	v_mfma_f32_16x16x32_bf16 v[122:125], v[138:141], v[184:187], v[122:125]
	v_mfma_f32_16x16x32_bf16 v[122:125], v[142:145], v[188:191], v[122:125]
	v_mfma_f32_16x16x32_bf16 v[110:113], v[130:133], v[192:195], v[110:113]
	v_mfma_f32_16x16x32_bf16 v[110:113], v[134:137], v[196:199], v[110:113]
	v_mfma_f32_16x16x32_bf16 v[106:109], v[138:141], v[192:195], v[106:109]
	v_mfma_f32_16x16x32_bf16 v[106:109], v[142:145], v[196:199], v[106:109]
	v_mfma_f32_16x16x32_bf16 v[94:97], v[130:133], v[200:203], v[94:97]
	v_mfma_f32_16x16x32_bf16 v[94:97], v[134:137], v[204:207], v[94:97]
	v_mfma_f32_16x16x32_bf16 v[90:93], v[138:141], v[200:203], v[90:93]
	v_mfma_f32_16x16x32_bf16 v[90:93], v[142:145], v[204:207], v[90:93]
	v_mfma_f32_16x16x32_bf16 v[78:81], v[130:133], v[208:211], v[78:81]
	v_mfma_f32_16x16x32_bf16 v[78:81], v[134:137], v[212:215], v[78:81]
	v_mfma_f32_16x16x32_bf16 v[74:77], v[138:141], v[208:211], v[74:77]
	v_mfma_f32_16x16x32_bf16 v[74:77], v[142:145], v[212:215], v[74:77]
	v_mfma_f32_16x16x32_bf16 v[118:121], v[146:149], v[184:187], v[118:121]
	v_mfma_f32_16x16x32_bf16 v[118:121], v[166:169], v[188:191], v[118:121]
	v_mfma_f32_16x16x32_bf16 v[114:117], v[170:173], v[184:187], v[114:117]
	v_mfma_f32_16x16x32_bf16 v[114:117], v[180:183], v[188:191], v[114:117]
	v_mfma_f32_16x16x32_bf16 v[102:105], v[146:149], v[192:195], v[102:105]
	v_mfma_f32_16x16x32_bf16 v[102:105], v[166:169], v[196:199], v[102:105]
	v_mfma_f32_16x16x32_bf16 v[98:101], v[170:173], v[192:195], v[98:101]
	v_mfma_f32_16x16x32_bf16 v[98:101], v[180:183], v[196:199], v[98:101]
	v_mfma_f32_16x16x32_bf16 v[86:89], v[146:149], v[200:203], v[86:89]
	v_mfma_f32_16x16x32_bf16 v[86:89], v[166:169], v[204:207], v[86:89]
	v_mfma_f32_16x16x32_bf16 v[82:85], v[170:173], v[200:203], v[82:85]
	v_mfma_f32_16x16x32_bf16 v[82:85], v[180:183], v[204:207], v[82:85]
	v_mfma_f32_16x16x32_bf16 v[70:73], v[146:149], v[208:211], v[70:73]
	v_mfma_f32_16x16x32_bf16 v[70:73], v[166:169], v[212:215], v[70:73]
	v_mfma_f32_16x16x32_bf16 v[66:69], v[170:173], v[208:211], v[66:69]
	v_mfma_f32_16x16x32_bf16 v[66:69], v[180:183], v[212:215], v[66:69]
	s_barrier
	s_add_i32 s50, s41, s31
	s_mov_b32 m0, s50
	ds_read_b128 v[184:187], v178 offset:16384
	ds_read_b128 v[188:191], v178 offset:17408
	ds_read_b128 v[192:195], v178 offset:18432
	ds_read_b128 v[196:199], v178 offset:19456
	ds_read_b128 v[200:203], v178 offset:20480
	ds_read_b128 v[204:207], v178 offset:21504
	ds_read_b128 v[208:211], v178 offset:22528
	ds_read_b128 v[212:215], v178 offset:23552
	global_load_lds_dwordx4 v152, s[26:27]
	s_add_i32 m0, s50, 0x2000
	s_add_u32 s50, s26, 0x2b0000
	s_addc_u32 s51, s27, 0
	s_add_i32 s52, s42, s31
	global_load_lds_dwordx4 v156, s[26:27]
	s_mov_b32 m0, s52
	global_load_lds_dwordx4 v152, s[50:51]
	s_add_i32 m0, s52, 0x2000
	s_nop 0
	global_load_lds_dwordx4 v156, s[50:51]
	s_mov_b32 m0, s33
	s_nop 0
	global_load_lds_dwordx4 v150, s[28:29]
	s_mov_b32 m0, s34
	s_nop 0
	global_load_lds_dwordx4 v154, s[28:29]
	s_waitcnt vmcnt(8)
	s_waitcnt lgkmcnt(0)
	s_barrier
	v_mfma_f32_16x16x32_bf16 v[62:65], v[130:133], v[184:187], v[62:65]
	v_mfma_f32_16x16x32_bf16 v[62:65], v[134:137], v[188:191], v[62:65]
	v_mfma_f32_16x16x32_bf16 v[58:61], v[138:141], v[184:187], v[58:61]
	v_mfma_f32_16x16x32_bf16 v[58:61], v[142:145], v[188:191], v[58:61]
	v_mfma_f32_16x16x32_bf16 v[46:49], v[130:133], v[192:195], v[46:49]
	v_mfma_f32_16x16x32_bf16 v[46:49], v[134:137], v[196:199], v[46:49]
	v_mfma_f32_16x16x32_bf16 v[42:45], v[138:141], v[192:195], v[42:45]
	v_mfma_f32_16x16x32_bf16 v[42:45], v[142:145], v[196:199], v[42:45]
	v_mfma_f32_16x16x32_bf16 v[30:33], v[130:133], v[200:203], v[30:33]
	v_mfma_f32_16x16x32_bf16 v[30:33], v[134:137], v[204:207], v[30:33]
	v_mfma_f32_16x16x32_bf16 v[26:29], v[138:141], v[200:203], v[26:29]
	v_mfma_f32_16x16x32_bf16 v[26:29], v[142:145], v[204:207], v[26:29]
	v_mfma_f32_16x16x32_bf16 v[14:17], v[130:133], v[208:211], v[14:17]
	v_mfma_f32_16x16x32_bf16 v[14:17], v[134:137], v[212:215], v[14:17]
	v_mfma_f32_16x16x32_bf16 v[10:13], v[138:141], v[208:211], v[10:13]
	v_mfma_f32_16x16x32_bf16 v[10:13], v[142:145], v[212:215], v[10:13]
	v_mfma_f32_16x16x32_bf16 v[54:57], v[146:149], v[184:187], v[54:57]
	v_mfma_f32_16x16x32_bf16 v[54:57], v[166:169], v[188:191], v[54:57]
	v_mfma_f32_16x16x32_bf16 v[50:53], v[170:173], v[184:187], v[50:53]
	v_mfma_f32_16x16x32_bf16 v[50:53], v[180:183], v[188:191], v[50:53]
	v_mfma_f32_16x16x32_bf16 v[38:41], v[146:149], v[192:195], v[38:41]
	v_mfma_f32_16x16x32_bf16 v[38:41], v[166:169], v[196:199], v[38:41]
	v_mfma_f32_16x16x32_bf16 v[34:37], v[170:173], v[192:195], v[34:37]
	v_mfma_f32_16x16x32_bf16 v[34:37], v[180:183], v[196:199], v[34:37]
	v_mfma_f32_16x16x32_bf16 v[22:25], v[146:149], v[200:203], v[22:25]
	v_mfma_f32_16x16x32_bf16 v[22:25], v[166:169], v[204:207], v[22:25]
	v_mfma_f32_16x16x32_bf16 v[18:21], v[170:173], v[200:203], v[18:21]
	v_mfma_f32_16x16x32_bf16 v[18:21], v[180:183], v[204:207], v[18:21]
	v_mfma_f32_16x16x32_bf16 v[6:9], v[146:149], v[208:211], v[6:9]
	v_mfma_f32_16x16x32_bf16 v[6:9], v[166:169], v[212:215], v[6:9]
	v_mfma_f32_16x16x32_bf16 v[2:5], v[170:173], v[208:211], v[2:5]
	v_mfma_f32_16x16x32_bf16 v[2:5], v[180:183], v[212:215], v[2:5]
	s_barrier
	s_add_i32 s50, 0, 0x18000
	s_add_i32 s51, 0, 0x1c000
	ds_read_b128 v[130:133], v246
	ds_read_b128 v[134:137], v246 offset:1024
	ds_read_b128 v[138:141], v246 offset:2048
	ds_read_b128 v[142:145], v246 offset:3072
	ds_read_b128 v[146:149], v247
	ds_read_b128 v[166:169], v247 offset:1024
	ds_read_b128 v[170:173], v247 offset:2048
	ds_read_b128 v[180:183], v247 offset:3072
	s_add_u32 s98, s28, 0x80
	s_addc_u32 s99, s29, 0
	s_add_u32 s28, s28, 0x2b0000
	s_addc_u32 s29, s29, 0
	s_mov_b32 m0, s35
	ds_read_b128 v[184:187], v178 offset:32768
	ds_read_b128 v[188:191], v178 offset:33792
	ds_read_b128 v[192:195], v178 offset:34816
	ds_read_b128 v[196:199], v178 offset:35840
	ds_read_b128 v[200:203], v178 offset:36864
	ds_read_b128 v[204:207], v178 offset:37888
	ds_read_b128 v[208:211], v178 offset:38912
	ds_read_b128 v[212:215], v178 offset:39936
	global_load_lds_dwordx4 v150, s[28:29]
	s_mov_b32 m0, s36
	s_nop 0
	global_load_lds_dwordx4 v154, s[28:29]
	s_waitcnt vmcnt(8)
	s_waitcnt lgkmcnt(0)
	s_barrier
	v_mfma_f32_16x16x32_bf16 v[126:129], v[130:133], v[184:187], v[126:129]
	v_mfma_f32_16x16x32_bf16 v[126:129], v[134:137], v[188:191], v[126:129]
	v_mfma_f32_16x16x32_bf16 v[122:125], v[138:141], v[184:187], v[122:125]
	v_mfma_f32_16x16x32_bf16 v[122:125], v[142:145], v[188:191], v[122:125]
	v_mfma_f32_16x16x32_bf16 v[110:113], v[130:133], v[192:195], v[110:113]
	v_mfma_f32_16x16x32_bf16 v[110:113], v[134:137], v[196:199], v[110:113]
	v_mfma_f32_16x16x32_bf16 v[106:109], v[138:141], v[192:195], v[106:109]
	v_mfma_f32_16x16x32_bf16 v[106:109], v[142:145], v[196:199], v[106:109]
	v_mfma_f32_16x16x32_bf16 v[94:97], v[130:133], v[200:203], v[94:97]
	v_mfma_f32_16x16x32_bf16 v[94:97], v[134:137], v[204:207], v[94:97]
	v_mfma_f32_16x16x32_bf16 v[90:93], v[138:141], v[200:203], v[90:93]
	v_mfma_f32_16x16x32_bf16 v[90:93], v[142:145], v[204:207], v[90:93]
	v_mfma_f32_16x16x32_bf16 v[78:81], v[130:133], v[208:211], v[78:81]
	v_mfma_f32_16x16x32_bf16 v[78:81], v[134:137], v[212:215], v[78:81]
	v_mfma_f32_16x16x32_bf16 v[74:77], v[138:141], v[208:211], v[74:77]
	v_mfma_f32_16x16x32_bf16 v[74:77], v[142:145], v[212:215], v[74:77]
	v_mfma_f32_16x16x32_bf16 v[118:121], v[146:149], v[184:187], v[118:121]
	v_mfma_f32_16x16x32_bf16 v[118:121], v[166:169], v[188:191], v[118:121]
	v_mfma_f32_16x16x32_bf16 v[114:117], v[170:173], v[184:187], v[114:117]
	v_mfma_f32_16x16x32_bf16 v[114:117], v[180:183], v[188:191], v[114:117]
	v_mfma_f32_16x16x32_bf16 v[102:105], v[146:149], v[192:195], v[102:105]
	v_mfma_f32_16x16x32_bf16 v[102:105], v[166:169], v[196:199], v[102:105]
	v_mfma_f32_16x16x32_bf16 v[98:101], v[170:173], v[192:195], v[98:101]
	v_mfma_f32_16x16x32_bf16 v[98:101], v[180:183], v[196:199], v[98:101]
	v_mfma_f32_16x16x32_bf16 v[86:89], v[146:149], v[200:203], v[86:89]
	v_mfma_f32_16x16x32_bf16 v[86:89], v[166:169], v[204:207], v[86:89]
	v_mfma_f32_16x16x32_bf16 v[82:85], v[170:173], v[200:203], v[82:85]
	v_mfma_f32_16x16x32_bf16 v[82:85], v[180:183], v[204:207], v[82:85]
	v_mfma_f32_16x16x32_bf16 v[70:73], v[146:149], v[208:211], v[70:73]
	v_mfma_f32_16x16x32_bf16 v[70:73], v[166:169], v[212:215], v[70:73]
	v_mfma_f32_16x16x32_bf16 v[66:69], v[170:173], v[208:211], v[66:69]
	v_mfma_f32_16x16x32_bf16 v[66:69], v[180:183], v[212:215], v[66:69]
	s_barrier
	s_add_i32 s28, s50, s31
	s_mov_b32 m0, s28
	ds_read_b128 v[184:187], v178 offset:49152
	ds_read_b128 v[188:191], v178 offset:50176
	ds_read_b128 v[192:195], v178 offset:51200
	ds_read_b128 v[196:199], v178 offset:52224
	ds_read_b128 v[200:203], v178 offset:53248
	ds_read_b128 v[204:207], v178 offset:54272
	ds_read_b128 v[208:211], v178 offset:55296
	ds_read_b128 v[212:215], v178 offset:56320
	s_add_u32 s26, s26, 0x80
	s_addc_u32 s27, s27, 0
	global_load_lds_dwordx4 v152, s[26:27]
	s_add_i32 m0, s28, 0x2000
	s_add_i32 s28, s51, s31
	global_load_lds_dwordx4 v156, s[26:27]
	s_add_u32 s26, s26, 0x2b0000
	s_addc_u32 s27, s27, 0
	s_mov_b32 m0, s28
	s_nop 0
	global_load_lds_dwordx4 v152, s[26:27]
	s_add_i32 m0, s28, 0x2000
	s_nop 0
	global_load_lds_dwordx4 v156, s[26:27]
	s_mov_b32 m0, s38
	s_nop 0
	global_load_lds_dwordx4 v150, s[98:99]
	s_mov_b32 m0, s39
	s_nop 0
	global_load_lds_dwordx4 v154, s[98:99]
	s_waitcnt vmcnt(8)
	s_waitcnt lgkmcnt(0)
	s_barrier
	v_mfma_f32_16x16x32_bf16 v[62:65], v[130:133], v[184:187], v[62:65]
	v_mfma_f32_16x16x32_bf16 v[62:65], v[134:137], v[188:191], v[62:65]
	v_mfma_f32_16x16x32_bf16 v[58:61], v[138:141], v[184:187], v[58:61]
	v_mfma_f32_16x16x32_bf16 v[58:61], v[142:145], v[188:191], v[58:61]
	v_mfma_f32_16x16x32_bf16 v[46:49], v[130:133], v[192:195], v[46:49]
	v_mfma_f32_16x16x32_bf16 v[46:49], v[134:137], v[196:199], v[46:49]
	v_mfma_f32_16x16x32_bf16 v[42:45], v[138:141], v[192:195], v[42:45]
	v_mfma_f32_16x16x32_bf16 v[42:45], v[142:145], v[196:199], v[42:45]
	v_mfma_f32_16x16x32_bf16 v[30:33], v[130:133], v[200:203], v[30:33]
	v_mfma_f32_16x16x32_bf16 v[30:33], v[134:137], v[204:207], v[30:33]
	v_mfma_f32_16x16x32_bf16 v[26:29], v[138:141], v[200:203], v[26:29]
	v_mfma_f32_16x16x32_bf16 v[26:29], v[142:145], v[204:207], v[26:29]
	v_mfma_f32_16x16x32_bf16 v[14:17], v[130:133], v[208:211], v[14:17]
	v_mfma_f32_16x16x32_bf16 v[14:17], v[134:137], v[212:215], v[14:17]
	v_mfma_f32_16x16x32_bf16 v[10:13], v[138:141], v[208:211], v[10:13]
	v_mfma_f32_16x16x32_bf16 v[10:13], v[142:145], v[212:215], v[10:13]
	v_mfma_f32_16x16x32_bf16 v[54:57], v[146:149], v[184:187], v[54:57]
	v_mfma_f32_16x16x32_bf16 v[54:57], v[166:169], v[188:191], v[54:57]
	v_mfma_f32_16x16x32_bf16 v[50:53], v[170:173], v[184:187], v[50:53]
	v_mfma_f32_16x16x32_bf16 v[50:53], v[180:183], v[188:191], v[50:53]
	v_mfma_f32_16x16x32_bf16 v[38:41], v[146:149], v[192:195], v[38:41]
	v_mfma_f32_16x16x32_bf16 v[38:41], v[166:169], v[196:199], v[38:41]
	v_mfma_f32_16x16x32_bf16 v[34:37], v[170:173], v[192:195], v[34:37]
	v_mfma_f32_16x16x32_bf16 v[34:37], v[180:183], v[196:199], v[34:37]
	v_mfma_f32_16x16x32_bf16 v[22:25], v[146:149], v[200:203], v[22:25]
	v_mfma_f32_16x16x32_bf16 v[22:25], v[166:169], v[204:207], v[22:25]
	v_mfma_f32_16x16x32_bf16 v[18:21], v[170:173], v[200:203], v[18:21]
	v_mfma_f32_16x16x32_bf16 v[18:21], v[180:183], v[204:207], v[18:21]
	v_mfma_f32_16x16x32_bf16 v[6:9], v[146:149], v[208:211], v[6:9]
	v_mfma_f32_16x16x32_bf16 v[6:9], v[166:169], v[212:215], v[6:9]
	v_mfma_f32_16x16x32_bf16 v[2:5], v[170:173], v[208:211], v[2:5]
	v_mfma_f32_16x16x32_bf16 v[2:5], v[180:183], v[212:215], v[2:5]
	s_barrier
	s_add_i32 s49, s49, 2
	s_add_u32 s24, s24, 0x100
	s_addc_u32 s25, s25, 0
	s_add_u32 s47, s47, 0x100
	s_addc_u32 s48, s48, 0
	s_cmpk_gt_u32 s49, 0xa9
	s_cbranch_scc0 .LBB0_1325
	s_and_b64 vcc, exec, s[10:11]
	s_cbranch_vccz .LBB0_1328
	s_barrier
